# wave role split (matrix-phase waves / vector-phase waves) applied to the GQA attention unit as well as the MLA unit
# speedup vs baseline: 1.0005x; 1.0005x over previous
; __device__ __forceinline__ float max3f(float a, float b, float c) { float r; asm("v_max3_f32 %0, %1, %2, %3" : "=v"(r) : "v"(a), "v"(b), "v"(c)); return r; }
; template <int GRP, bool has_next> __device__ __forceinline__ void att_step(const AttCtx<GRP>& C, AttState<GRP>& S, int s, f32x16& P0, f32x16& P1, f32x16& PN0, f32x16& PN1, u32x4& kreg, u32x4& preg, u32x4& vreg) {
;     ...
;     if ((t & 7) == 0) {
;         float ma = max3f(P0[0], P0[1], P0[2]), mb = max3f(P0[3], P0[4], P0[5]), mc = max3f(P1[0], P1[1], P1[2]), md = max3f(P1[3], P1[4], P1[5]);
;         ma = max3f(ma, P0[6], P0[7]); mb = max3f(mb, P0[8], P0[9]); mc = max3f(mc, P1[6], P1[7]); md = max3f(md, P1[8], P1[9]);
;         ma = max3f(ma, P0[10], P0[11]); mb = max3f(mb, P0[12], P0[13]); mc = max3f(mc, P1[10], P1[11]); md = max3f(md, P1[12], P1[13]);
;         ma = max3f(ma, P0[14], P0[15]); mc = max3f(mc, P1[14], P1[15]); ma = max3f(ma, mb, mc); mb = md;
;         const float mx = xhalf_max(max2f(ma, mb));
;         const int up = __any(mx > THR), dn = (t == 0) ? __any(mx < -THR) : 0;
; template <int GRP> ...
;     ...
;     u32x4 kA, pA = {0u, 0u, 0u, 0u}, vA;
;     AttState<GRP> S;
;     S.o0 = (f32x16){}; S.o1 = (f32x16){}; S.mhat = 0.f; S.lrun = 0.f; S.ssq = 0.f; S.refnz = 0;
; #pragma unroll
;     for (int i = 0; i < 16; ++i) S.pw[i] = 0u;
;     { u32x4 kB, pB = {0u, 0u, 0u, 0u};
;       att_ldk<GRP>(C, 0, kA, pA); att_ldk<GRP>(C, 1, kB, pB); att_ldv<GRP>(C, 0, vA);
;       att_stk<GRP>(C, 0, kA, pA); att_stk<GRP>(C, 1, kB, pB); att_stv<GRP>(C, 0, vA); }
;     att_ldk<GRP>(C, 2, kA, pA); att_ldv<GRP>(C, 1, vA);
; #pragma unroll
;     for (int ks = 0; ks < NKS; ++ks) S.qr[ks] = *(const bf16x8*)(Q + C.qrow * QP + C.h0 * DK + ks * 16 + hi * 8);
;     ATT_BAR();
;     f32x16 pa0 = {}, pa1 = {}, pb0 = {}, pb1 = {};
;     {
;         bf16x8 kf[2 * NKS]; att_kfrag<GRP, 0, NKS>(C, 0, kf);
; #pragma unroll
;         for (int ks = 0; ks < NKS; ++ks) { pa0 = __builtin_amdgcn_mfma_f32_32x32x16_bf16(kf[2 * ks], S.qr[ks], pa0, 0, 0, 0); pa1 = __builtin_amdgcn_mfma_f32_32x32x16_bf16(kf[2 * ks + 1], S.qr[ks], pa1, 0, 0, 0); }
;     }
;     if (wid >= 4) __builtin_amdgcn_s_setprio(1);
;     asm volatile("s_nop 15\n\ts_nop 7" : "+v"(pa0), "+v"(pa1));
;     for (int s = 0; s < NSTEP - 2; s += 2) { att_step<GRP, true>(C, S, s, pa0, pa1, pb0, pb1, kA, pA, vA); att_step<GRP, true>(C, S, s + 1, pb0, pb1, pa0, pa1, kA, pA, vA); }
.LBB0_807:
	v_lshlrev_b32_e32 v8, 3, v3
	v_mad_u32_u24 v10, v6, s37, v96
	v_lshlrev_b64 v[6:7], 11, v[132:133]
	v_mov_b32_e32 v9, v97
	v_mad_u64_u32 v[0:1], s[6:7], v0, s37, v[2:3]
	v_lshl_add_u64 v[134:135], s[48:49], 0, v[6:7]
	v_lshlrev_b32_e32 v96, 1, v8
	v_mov_b32_e32 v152, 0
	s_mov_b32 s62, 0
	v_cmp_eq_u32_e64 s[0:1], 0, v3
	v_lshlrev_b32_e32 v136, 2, v3
	v_lshl_add_u64 v[142:143], v[134:135], 0, v[8:9]
	v_lshl_add_u64 v[144:145], v[4:5], 0, v[96:97]
	v_add_u32_e32 v146, 0, v10
	v_add_u32_e32 v147, 0, v0
	v_mov_b32_e32 v137, 0
	s_mov_b32 s61, 0
	v_mov_b32_e32 v148, 0
	v_mov_b32_e32 v0, 0
	v_mov_b32_e32 v1, v152
	v_mov_b32_e32 v2, v152
	v_mov_b32_e32 v3, v152
	v_mov_b32_e32 v4, v152
	v_mov_b32_e32 v5, v152
	v_mov_b32_e32 v6, v152
	v_mov_b32_e32 v7, v152
	v_mov_b32_e32 v8, v152
	v_mov_b32_e32 v9, v152
	v_mov_b32_e32 v10, v152
	v_mov_b32_e32 v11, v152
	v_mov_b32_e32 v12, v152
	v_mov_b32_e32 v13, v152
	v_mov_b32_e32 v14, v152
	v_mov_b32_e32 v15, v152
	v_mov_b32_e32 v16, 0
	v_mov_b32_e32 v17, v152
	v_mov_b32_e32 v18, v152
	v_mov_b32_e32 v19, v152
	v_mov_b32_e32 v20, v152
	v_mov_b32_e32 v21, v152
	v_mov_b32_e32 v22, v152
	v_mov_b32_e32 v23, v152
	v_mov_b32_e32 v24, v152
	v_mov_b32_e32 v25, v152
	v_mov_b32_e32 v26, v152
	v_mov_b32_e32 v27, v152
	v_mov_b32_e32 v28, v152
	v_mov_b32_e32 v29, v152
	v_mov_b32_e32 v30, v152
	v_mov_b32_e32 v31, v152
	s_nop 15
	s_nop 7
	s_waitcnt lgkmcnt(0)
	s_barrier
	v_readfirstlane_b32 s93, v254
	s_cmpk_gt_u32 s93, 0xff
	s_cbranch_scc1 .Lgqa_T_entry
	s_setprio 1
	s_and_b32 s10, s61, 6
	s_cmp_lg_u32 s10, 0
	s_cbranch_scc1 .Lgqa_nomax1001
	v_max3_f32 v96, v48, v49, v50
	v_max3_f32 v99, v32, v33, v34
	v_max3_f32 v98, v51, v52, v53
	v_max3_f32 v153, v35, v36, v37
	s_and_b32 s10, s61, 56
	v_max3_f32 v96, v96, v54, v55
	v_max3_f32 v99, v99, v38, v39
	v_max3_f32 v98, v98, v56, v57
	v_max3_f32 v153, v153, v40, v41
	s_cmp_eq_u32 s10, 0
	v_max3_f32 v96, v96, v58, v59
	v_max3_f32 v99, v99, v42, v43
	v_max3_f32 v98, v98, v60, v61
	v_max3_f32 v153, v153, v44, v45
	s_cselect_b64 s[6:7], -1, 0
	v_max3_f32 v96, v96, v62, v63
	v_max3_f32 v99, v99, v46, v47
	s_cmp_lg_u32 s10, 0
	v_max3_f32 v96, v96, v98, v99
	s_nop 0
	v_max_f32_e32 v96, v96, v153
	s_nop 0
	v_mov_b32_e32 v98, v96
	s_nop 1
	v_permlane32_swap_b32_e32 v96, v98
	v_max_f32_e32 v98, v98, v98
	v_max_f32_e32 v96, v96, v96
	v_max_f32_e32 v96, v96, v98
	v_cmp_lt_f32_e32 vcc, s54, v96
	v_mov_b32_e32 v98, 0
	s_cbranch_scc1 .Lgqa_mx1002
	v_cmp_gt_f32_e64 s[10:11], s55, v96
	s_cmp_lg_u64 s[10:11], 0
	s_cselect_b64 s[10:11], -1, 0
	v_cndmask_b32_e64 v98, 0, 1, s[10:11]

; __device__ __forceinline__ float max2f(float a, float b) { float r; asm("v_max_f32_e32 %0, %1, %2" : "=v"(r) : "v"(a), "v"(b)); return r; }
; template <int GRP, bool has_next> __device__ __forceinline__ void att_step(const AttCtx<GRP>& C, AttState<GRP>& S, int s, f32x16& P0, f32x16& P1, f32x16& PN0, f32x16& PN1, u32x4& kreg, u32x4& preg, u32x4& vreg) {
;     ...
;         att_kfrag<GRP, 0, NK0>(C, (s + 1) & 1, kfa);
;     }
;     if (has_next) { PN0 = __builtin_amdgcn_mfma_f32_32x32x16_bf16(kfa[0], S.qr[0], (f32x16){}, 0, 0, 0); PN1 = __builtin_amdgcn_mfma_f32_32x32x16_bf16(kfa[1], S.qr[0], (f32x16){}, 0, 0, 0); }
;     if ((t & 7) == 0) {
;         float ma = max3f(P0[0], P0[1], P0[2]), mb = max3f(P0[3], P0[4], P0[5]), mc = max3f(P1[0], P1[1], P1[2]), md = max3f(P1[3], P1[4], P1[5]);
;         ma = max3f(ma, P0[6], P0[7]); mb = max3f(mb, P0[8], P0[9]); mc = max3f(mc, P1[6], P1[7]); md = max3f(md, P1[8], P1[9]);
;         ma = max3f(ma, P0[10], P0[11]); mb = max3f(mb, P0[12], P0[13]); mc = max3f(mc, P1[10], P1[11]); md = max3f(md, P1[12], P1[13]);
;         ma = max3f(ma, P0[14], P0[15]); mc = max3f(mc, P1[14], P1[15]); ma = max3f(ma, mb, mc); mb = md;
;         const float mx = xhalf_max(max2f(ma, mb));
;         const int up = __any(mx > THR), dn = (t == 0) ? __any(mx < -THR) : 0;
;         if (up | dn) {
;             const float dl = ceilf((t == 0) ? mx : fmaxf(mx, 0.f));
;             const float f = (t == 0) ? 0.f : __builtin_amdgcn_exp2f(-dl);
;             S.mhat += dl; S.lrun *= f;
; #pragma unroll
;             for (int r = 0; r < 16; ++r) { P0[r] -= dl; P1[r] -= dl; S.o0[r] *= f; S.o1[r] *= f; }
;             S.refnz = __any(S.mhat != 0.f);
;         }
;     }
;     __builtin_amdgcn_sched_barrier(0);
;     const unsigned mbits = (t == 63 || C.hi != 0) ? 0u : (__float_as_uint(-S.mhat) >> 16);
;     const u32x4 qxw = {mbits, 0u, 0u, 0u}; const bf16x8 qx = __builtin_bit_cast(bf16x8, qxw);
;     const bf16x8 ones = {0x3f80, 0x3f80, 0x3f80, 0x3f80, 0x3f80, 0x3f80, 0x3f80, 0x3f80};
;     constexpr int NE = NKS - 1;
;     float ra = 0.f, rb = 0.f, rc = 0.f, rd = 0.f;
;     ...
; #pragma unroll
;     for (int c = 1; c < NKS; ++c) {
;         if (has_next) {
;             if (c == NK0) att_kfrag<GRP, NK0, NK1>(C, (s + 1) & 1, kfb);
;             const bf16x8 a0 = c < NK0 ? kfa[2 * c] : kfb[2 * (c - NK0)], a1 = c < NK0 ? kfa[2 * c + 1] : kfb[2 * (c - NK0) + 1];
.Lgqa_nomax1001:
	v_exp_f32_e32 v48, v48
	v_exp_f32_e32 v49, v49
	v_exp_f32_e32 v50, v50
	v_exp_f32_e32 v51, v51
	v_cvt_pk_bf16_f32 v216, v48, v49
	v_exp_f32_e32 v52, v52
	v_exp_f32_e32 v53, v53
	v_cvt_pk_bf16_f32 v217, v50, v51
	v_exp_f32_e32 v54, v54
	v_exp_f32_e32 v55, v55
	v_add_f32_e32 v248, v48, v52
	v_add_f32_e32 v249, v49, v53
	v_cvt_pk_bf16_f32 v218, v52, v53
	v_exp_f32_e32 v56, v56
	v_exp_f32_e32 v57, v57
	v_add_f32_e32 v250, v50, v54
	v_add_f32_e32 v251, v51, v55
	v_cvt_pk_bf16_f32 v219, v54, v55
	v_exp_f32_e32 v58, v58
	v_exp_f32_e32 v59, v59
	v_add_f32_e32 v248, v248, v56
	v_add_f32_e32 v249, v249, v57
	v_cvt_pk_bf16_f32 v220, v56, v57
	v_exp_f32_e32 v60, v60
	v_exp_f32_e32 v61, v61
	v_add_f32_e32 v250, v250, v58
	v_add_f32_e32 v251, v251, v59
	v_cvt_pk_bf16_f32 v221, v58, v59
	v_exp_f32_e32 v62, v62
	v_exp_f32_e32 v63, v63
	v_add_f32_e32 v248, v248, v60
	v_add_f32_e32 v249, v249, v61
	v_cvt_pk_bf16_f32 v222, v60, v61
	v_exp_f32_e32 v32, v32
	v_exp_f32_e32 v33, v33
	v_add_f32_e32 v250, v250, v62
	v_add_f32_e32 v251, v251, v63
	v_cvt_pk_bf16_f32 v223, v62, v63
	v_exp_f32_e32 v34, v34
	v_exp_f32_e32 v35, v35
	v_add_f32_e32 v248, v248, v32
	v_add_f32_e32 v249, v249, v33
	v_cvt_pk_bf16_f32 v224, v32, v33
	v_exp_f32_e32 v36, v36
	v_exp_f32_e32 v37, v37
	v_add_f32_e32 v250, v250, v34
	v_add_f32_e32 v251, v251, v35
	v_cvt_pk_bf16_f32 v225, v34, v35
	v_exp_f32_e32 v38, v38
	v_exp_f32_e32 v39, v39
	v_add_f32_e32 v248, v248, v36
	v_add_f32_e32 v249, v249, v37
	v_cvt_pk_bf16_f32 v226, v36, v37
	v_exp_f32_e32 v40, v40
	v_exp_f32_e32 v41, v41
	v_add_f32_e32 v250, v250, v38
	v_add_f32_e32 v251, v251, v39
	v_cvt_pk_bf16_f32 v227, v38, v39
	v_exp_f32_e32 v42, v42
	v_exp_f32_e32 v43, v43
	v_add_f32_e32 v248, v248, v40
	v_add_f32_e32 v249, v249, v41
	v_cvt_pk_bf16_f32 v228, v40, v41
	v_exp_f32_e32 v44, v44
	v_exp_f32_e32 v45, v45
	v_add_f32_e32 v250, v250, v42
	v_add_f32_e32 v251, v251, v43
	v_cvt_pk_bf16_f32 v229, v42, v43
	v_exp_f32_e32 v46, v46
	v_exp_f32_e32 v47, v47
	v_add_f32_e32 v248, v248, v44
	v_add_f32_e32 v249, v249, v45
	v_cvt_pk_bf16_f32 v230, v44, v45
	v_add_f32_e32 v250, v250, v46
	v_add_f32_e32 v251, v251, v47
	v_cvt_pk_bf16_f32 v231, v46, v47
	v_add_f32_e32 v248, v248, v249
	v_add_f32_e32 v250, v250, v251
	v_add_f32_e32 v248, v248, v250
	v_add_f32_e32 v148, v148, v248
.Lgqa_L_loop:
	ds_read_b128 v[156:159], v149 offset:13312
	ds_read_b128 v[160:163], v149 offset:19968
	ds_read_b128 v[164:167], v149 offset:13344
	ds_read_b128 v[168:171], v149 offset:20000
	ds_read_b128 v[172:175], v149 offset:13376
	ds_read_b128 v[176:179], v149 offset:20032
	s_waitcnt lgkmcnt(5)
	v_mfma_f32_32x32x16_bf16 v[80:95], v[156:159], v[112:115], 0
	ds_read_b128 v[156:159], v149 offset:13408
	s_waitcnt lgkmcnt(5)
	v_mfma_f32_32x32x16_bf16 v[64:79], v[160:163], v[112:115], 0
	ds_read_b128 v[160:163], v149 offset:20064
	s_waitcnt lgkmcnt(5)
	v_mfma_f32_32x32x16_bf16 v[80:95], v[164:167], v[108:111], v[80:95]
	ds_read_b128 v[232:235], v146 offset:26624
	s_waitcnt lgkmcnt(5)
	v_mfma_f32_32x32x16_bf16 v[64:79], v[168:171], v[108:111], v[64:79]
	ds_read_b128 v[236:239], v146 offset:31232
	s_waitcnt lgkmcnt(5)
	v_mfma_f32_32x32x16_bf16 v[80:95], v[172:175], v[104:107], v[80:95]
	ds_read_b128 v[240:243], v146 offset:26656
	s_waitcnt lgkmcnt(5)
	v_mfma_f32_32x32x16_bf16 v[64:79], v[176:179], v[104:107], v[64:79]
	ds_read_b128 v[244:247], v146 offset:31264
	s_waitcnt lgkmcnt(5)
	v_mfma_f32_32x32x16_bf16 v[80:95], v[156:159], v[100:103], v[80:95]
	s_waitcnt lgkmcnt(4)
	v_mfma_f32_32x32x16_bf16 v[64:79], v[160:163], v[100:103], v[64:79]
	s_cmp_eq_u32 s62, 0
	s_cbranch_scc1 .Lgqa_nrz1003
	v_xor_b32_e32 v195, 0x80000000, v152
	s_mov_b32 s18, s16
	s_mov_b32 s19, s16
	s_mov_b32 s17, s16
	v_mov_b64_e32 v[182:183], s[18:19]
	v_mov_b64_e32 v[180:181], s[16:17]
	s_mov_b64 vcc, s[0:1]
	v_cndmask_b32_sdwa v96, v97, v195, vcc dst_sel:DWORD dst_unused:UNUSED_PAD src0_sel:DWORD src1_sel:WORD_1
	v_mov_b32_e32 v98, v97
	v_mov_b32_e32 v99, v97
	s_nop 1
	v_mfma_f32_32x32x16_bf16 v[80:95], v[180:183], v[96:99], v[80:95]
	v_mfma_f32_32x32x16_bf16 v[64:79], v[180:183], v[96:99], v[64:79]
.Lgqa_nrz1003:
	s_waitcnt lgkmcnt(3)
	v_mfma_f32_32x32x16_bf16 v[16:31], v[232:235], v[216:219], v[16:31]
	ds_read_b128 v[232:235], v146 offset:26688
	s_waitcnt lgkmcnt(3)
	v_mfma_f32_32x32x16_bf16 v[0:15], v[236:239], v[216:219], v[0:15]
	ds_read_b128 v[236:239], v146 offset:31296
	s_waitcnt lgkmcnt(3)
	v_mfma_f32_32x32x16_bf16 v[16:31], v[240:243], v[220:223], v[16:31]
	ds_read_b128 v[240:243], v146 offset:26720
	s_waitcnt lgkmcnt(3)
	v_mfma_f32_32x32x16_bf16 v[0:15], v[244:247], v[220:223], v[0:15]
	ds_read_b128 v[244:247], v146 offset:31328
	s_waitcnt lgkmcnt(3)
	v_mfma_f32_32x32x16_bf16 v[16:31], v[232:235], v[224:227], v[16:31]
	s_waitcnt lgkmcnt(2)
	v_mfma_f32_32x32x16_bf16 v[0:15], v[236:239], v[224:227], v[0:15]
	s_waitcnt lgkmcnt(1)
	v_mfma_f32_32x32x16_bf16 v[16:31], v[240:243], v[228:231], v[16:31]
	s_waitcnt lgkmcnt(0)
	v_mfma_f32_32x32x16_bf16 v[0:15], v[244:247], v[228:231], v[0:15]
	s_add_i32 s88, s61, 3
	s_lshr_b32 s89, s88, 6
	s_add_i32 s89, s89, s60
	s_lshl_b32 s89, s89, 4
	s_and_b32 s89, s89, 0xffffffc0
	s_and_b32 s88, s88, 63
	s_or_b32 s88, s89, s88
	s_lshl_b32 s88, s88, 12
	s_ashr_i32 s89, s88, 31
	s_add_i32 s84, s61, 2
	s_lshr_b32 s85, s84, 6
	s_add_i32 s85, s85, s60
	s_lshl_b32 s85, s85, 4
	s_and_b32 s85, s85, 0xffffffc0
	s_and_b32 s84, s84, 63
	s_or_b32 s84, s85, s84
	s_lshl_b32 s84, s84, 12
	s_ashr_i32 s85, s84, 31
	s_waitcnt vmcnt(1)
	ds_write_b128 v150, v[116:119]
	v_lshl_add_u64 v[192:193], s[88:89], 1, v[140:141]
	s_waitcnt vmcnt(0)
; template <int GRP, bool has_next> __device__ __forceinline__ void att_step(const AttCtx<GRP>& C, AttState<GRP>& S, int s, f32x16& P0, f32x16& P1, f32x16& PN0, f32x16& PN1, u32x4& kreg, u32x4& preg, u32x4& vreg) {
;     ...
;     if (has_next) {
;         if (t == 63) {
; #pragma unroll
;             for (int ks = 0; ks < NKS; ++ks) S.qr[ks] = *(const bf16x8*)(C.Q + C.qrow * QP + (h + 1) * DK + ks * 16 + C.hi * 8);
;         }
;         att_kfrag<GRP, 0, NK0>(C, (s + 1) & 1, kfa);
;     }
;     if (has_next) { PN0 = __builtin_amdgcn_mfma_f32_32x32x16_bf16(kfa[0], S.qr[0], (f32x16){}, 0, 0, 0); PN1 = __builtin_amdgcn_mfma_f32_32x32x16_bf16(kfa[1], S.qr[0], (f32x16){}, 0, 0, 0); }
;     if ((t & 7) == 0) {
;         float ma = max3f(P0[0], P0[1], P0[2]), mb = max3f(P0[3], P0[4], P0[5]), mc = max3f(P1[0], P1[1], P1[2]), md = max3f(P1[3], P1[4], P1[5]);
;         ma = max3f(ma, P0[6], P0[7]); mb = max3f(mb, P0[8], P0[9]); mc = max3f(mc, P1[6], P1[7]); md = max3f(md, P1[8], P1[9]);
;         ma = max3f(ma, P0[10], P0[11]); mb = max3f(mb, P0[12], P0[13]); mc = max3f(mc, P1[10], P1[11]); md = max3f(md, P1[12], P1[13]);
;         ma = max3f(ma, P0[14], P0[15]); mc = max3f(mc, P1[14], P1[15]); ma = max3f(ma, mb, mc); mb = md;
;         const float mx = xhalf_max(max2f(ma, mb));
;         const int up = __any(mx > THR), dn = (t == 0) ? __any(mx < -THR) : 0;
;         if (up | dn) {
;             const float dl = ceilf((t == 0) ? mx : fmaxf(mx, 0.f));
;             const float f = (t == 0) ? 0.f : __builtin_amdgcn_exp2f(-dl);
;             S.mhat += dl; S.lrun *= f;
; #pragma unroll
;             for (int r = 0; r < 16; ++r) { P0[r] -= dl; P1[r] -= dl; S.o0[r] *= f; S.o1[r] *= f; }
;             S.refnz = __any(S.mhat != 0.f);
;         }
;     }
;     __builtin_amdgcn_sched_barrier(0);
;     const unsigned mbits = (t == 63 || C.hi != 0) ? 0u : (__float_as_uint(-S.mhat) >> 16);
;     const u32x4 qxw = {mbits, 0u, 0u, 0u}; const bf16x8 qx = __builtin_bit_cast(bf16x8, qxw);
;     const bf16x8 ones = {0x3f80, 0x3f80, 0x3f80, 0x3f80, 0x3f80, 0x3f80, 0x3f80, 0x3f80};
;     constexpr int NE = NKS - 1;
;     float ra = 0.f, rb = 0.f, rc = 0.f, rd = 0.f;
;     ...
; #pragma unroll
;     for (int c = 1; c < NKS; ++c) {
;         if (has_next) {
;             if (c == NK0) att_kfrag<GRP, NK0, NK1>(C, (s + 1) & 1, kfb);
	ds_write_b128 v147, v[120:123] offset:35840
	v_lshl_add_u64 v[190:191], s[84:85], 1, v[138:139]
	global_load_dwordx4 v[116:119], v[192:193], off
	global_load_dwordx4 v[124:127], v[190:191], off
	v_exp_f32_e32 v80, v80
	v_exp_f32_e32 v81, v81
	v_exp_f32_e32 v82, v82
	v_exp_f32_e32 v83, v83
	v_cvt_pk_bf16_f32 v216, v80, v81
	v_exp_f32_e32 v84, v84
	v_exp_f32_e32 v85, v85
	v_cvt_pk_bf16_f32 v217, v82, v83
	v_exp_f32_e32 v86, v86
	v_exp_f32_e32 v87, v87
	v_add_f32_e32 v248, v80, v84
	v_add_f32_e32 v249, v81, v85
	v_cvt_pk_bf16_f32 v218, v84, v85
	v_exp_f32_e32 v88, v88
	v_exp_f32_e32 v89, v89
	v_add_f32_e32 v250, v82, v86
	v_add_f32_e32 v251, v83, v87
	v_cvt_pk_bf16_f32 v219, v86, v87
	v_exp_f32_e32 v90, v90
	v_exp_f32_e32 v91, v91
	v_add_f32_e32 v248, v248, v88
	v_add_f32_e32 v249, v249, v89
	v_cvt_pk_bf16_f32 v220, v88, v89
	v_exp_f32_e32 v92, v92
	v_exp_f32_e32 v93, v93
	v_add_f32_e32 v250, v250, v90
	v_add_f32_e32 v251, v251, v91
	v_cvt_pk_bf16_f32 v221, v90, v91
	v_exp_f32_e32 v94, v94
	v_exp_f32_e32 v95, v95
	v_add_f32_e32 v248, v248, v92
	v_add_f32_e32 v249, v249, v93
	v_cvt_pk_bf16_f32 v222, v92, v93
	v_exp_f32_e32 v64, v64
	v_exp_f32_e32 v65, v65
	v_add_f32_e32 v250, v250, v94
	v_add_f32_e32 v251, v251, v95
	v_cvt_pk_bf16_f32 v223, v94, v95
	v_exp_f32_e32 v66, v66
	v_exp_f32_e32 v67, v67
	v_add_f32_e32 v248, v248, v64
	v_add_f32_e32 v249, v249, v65
	v_cvt_pk_bf16_f32 v224, v64, v65
	v_exp_f32_e32 v68, v68
	v_exp_f32_e32 v69, v69
	v_add_f32_e32 v250, v250, v66
	v_add_f32_e32 v251, v251, v67
	v_cvt_pk_bf16_f32 v225, v66, v67
	v_exp_f32_e32 v70, v70
	v_exp_f32_e32 v71, v71
	v_add_f32_e32 v248, v248, v68
	v_add_f32_e32 v249, v249, v69
	v_cvt_pk_bf16_f32 v226, v68, v69
	v_exp_f32_e32 v72, v72
	v_exp_f32_e32 v73, v73
	v_add_f32_e32 v250, v250, v70
	v_add_f32_e32 v251, v251, v71
	v_cvt_pk_bf16_f32 v227, v70, v71
	v_exp_f32_e32 v74, v74
	v_exp_f32_e32 v75, v75
	v_add_f32_e32 v248, v248, v72
	v_add_f32_e32 v249, v249, v73
	v_cvt_pk_bf16_f32 v228, v72, v73
	v_exp_f32_e32 v76, v76
	v_exp_f32_e32 v77, v77
	v_add_f32_e32 v250, v250, v74
	v_add_f32_e32 v251, v251, v75
	v_cvt_pk_bf16_f32 v229, v74, v75
	v_exp_f32_e32 v78, v78
	v_exp_f32_e32 v79, v79
	v_add_f32_e32 v248, v248, v76
	v_add_f32_e32 v249, v249, v77
	v_cvt_pk_bf16_f32 v230, v76, v77
	v_add_f32_e32 v250, v250, v78
	v_add_f32_e32 v251, v251, v79
	v_cvt_pk_bf16_f32 v231, v78, v79
	v_add_f32_e32 v248, v248, v249
	v_add_f32_e32 v250, v250, v251
	v_add_f32_e32 v248, v248, v250
	v_add_f32_e32 v148, v148, v248
	s_waitcnt lgkmcnt(0)
	s_barrier
	s_add_i32 s68, s61, 1
	s_lshr_b32 s10, s61, 6
	s_or_b32 s69, s10, s60
	s_and_b32 s10, s68, 63
	s_cmp_eq_u32 s10, 63
	s_cselect_b64 s[86:87], -1, 0
	s_cmp_lg_u64 s[86:87], 0
	s_cbranch_scc0 .Lgqa_noq1004
	s_lshl_b32 s88, s69, 6
	s_ashr_i32 s89, s88, 31
	v_lshl_add_u64 v[192:193], s[88:89], 1, v[144:145]
	global_load_dwordx4 v[112:115], v[192:193], off offset:128
	global_load_dwordx4 v[108:111], v[192:193], off offset:160
	global_load_dwordx4 v[104:107], v[192:193], off offset:192
	global_load_dwordx4 v[100:103], v[192:193], off offset:224
	s_waitcnt vmcnt(0)
.Lgqa_noq1004:
	ds_read_b128 v[156:159], v149 offset:0
	ds_read_b128 v[160:163], v149 offset:6656
	ds_read_b128 v[164:167], v149 offset:32
	ds_read_b128 v[168:171], v149 offset:6688
	ds_read_b128 v[172:175], v149 offset:64
	ds_read_b128 v[176:179], v149 offset:6720
	s_waitcnt lgkmcnt(5)
	v_mfma_f32_32x32x16_bf16 v[48:63], v[156:159], v[112:115], 0
	ds_read_b128 v[156:159], v149 offset:96
	s_waitcnt lgkmcnt(5)
	v_mfma_f32_32x32x16_bf16 v[32:47], v[160:163], v[112:115], 0
	ds_read_b128 v[160:163], v149 offset:6752
	s_waitcnt lgkmcnt(5)
	v_mfma_f32_32x32x16_bf16 v[48:63], v[164:167], v[108:111], v[48:63]
	ds_read_b128 v[232:235], v146 offset:35840
	s_waitcnt lgkmcnt(5)
	v_mfma_f32_32x32x16_bf16 v[32:47], v[168:171], v[108:111], v[32:47]
	ds_read_b128 v[236:239], v146 offset:40448
	s_waitcnt lgkmcnt(5)
	v_mfma_f32_32x32x16_bf16 v[48:63], v[172:175], v[104:107], v[48:63]
	ds_read_b128 v[240:243], v146 offset:35872
	s_waitcnt lgkmcnt(5)
	v_mfma_f32_32x32x16_bf16 v[32:47], v[176:179], v[104:107], v[32:47]
	ds_read_b128 v[244:247], v146 offset:40480
	s_waitcnt lgkmcnt(5)
	v_mfma_f32_32x32x16_bf16 v[48:63], v[156:159], v[100:103], v[48:63]
	s_waitcnt lgkmcnt(4)
	v_mfma_f32_32x32x16_bf16 v[32:47], v[160:163], v[100:103], v[32:47]
	s_cmp_eq_u32 s62, 0
	s_cbranch_scc1 .Lgqa_nrz1005
	s_cmp_lg_u64 s[86:87], 0
	s_cbranch_scc1 .Lgqa_nrz1005
	v_xor_b32_e32 v195, 0x80000000, v152
	s_mov_b32 s18, s16
	s_mov_b32 s19, s16
	s_mov_b32 s17, s16
	v_mov_b64_e32 v[182:183], s[18:19]
	v_mov_b64_e32 v[180:181], s[16:17]
	s_mov_b64 vcc, s[0:1]
	v_cndmask_b32_sdwa v96, v97, v195, vcc dst_sel:DWORD dst_unused:UNUSED_PAD src0_sel:DWORD src1_sel:WORD_1
	v_mov_b32_e32 v98, v97
	v_mov_b32_e32 v99, v97
	s_nop 1
	v_mfma_f32_32x32x16_bf16 v[48:63], v[180:183], v[96:99], v[48:63]
	v_mfma_f32_32x32x16_bf16 v[32:47], v[180:183], v[96:99], v[32:47]
; __device__ __forceinline__ unsigned cvtpk(float lo, float hi) { f32x2_t v = {lo, hi}; bf16x2_t b = __builtin_convertvector(v, bf16x2_t); return __builtin_bit_cast(unsigned, b); }
; __device__ __forceinline__ float xhalf_sum(float m) { auto rr = __builtin_amdgcn_permlane32_swap(__float_as_uint(m), __float_as_uint(m), false, false); return __uint_as_float(rr[0]) + __uint_as_float(rr[1]); }
; template <int GRP> __device__ __forceinline__ void att_pv(AttState<GRP>& S, const bf16x8 (&vf)[8]) {
; #pragma unroll
;     for (int ks = 0; ks < 4; ++ks) { const u32x4 w = {S.pw[4 * ks], S.pw[4 * ks + 1], S.pw[4 * ks + 2], S.pw[4 * ks + 3]}; const bf16x8 pb = __builtin_bit_cast(bf16x8, w);
;         S.o0 = __builtin_amdgcn_mfma_f32_32x32x16_bf16(vf[2 * ks], pb, S.o0, 0, 0, 0); S.o1 = __builtin_amdgcn_mfma_f32_32x32x16_bf16(vf[2 * ks + 1], pb, S.o1, 0, 0, 0); }
; }
; template <int GRP> __device__ __forceinline__ void att_finish_head(const AttCtx<GRP>& C, AttState<GRP>& S, int h) {
;     const float inv = 1.0f / xhalf_sum(S.lrun);
;     bf16_t* orow = C.O + C.qrow * 1024 + GRP * 512 + h * 64 + 4 * C.hi;
; #pragma unroll
;     for (int rr = 0; rr < 4; ++rr) {
;         const f32x4 v0 = (f32x4){S.o0[4 * rr], S.o0[4 * rr + 1], S.o0[4 * rr + 2], S.o0[4 * rr + 3]} * inv, v1 = (f32x4){S.o1[4 * rr], S.o1[4 * rr + 1], S.o1[4 * rr + 2], S.o1[4 * rr + 3]} * inv;
;         S.ssq += (v0[0] * v0[0] + v0[1] * v0[1]) + (v0[2] * v0[2] + v0[3] * v0[3]) + (v1[0] * v1[0] + v1[1] * v1[1]) + (v1[2] * v1[2] + v1[3] * v1[3]);
;         u32x2 s0, s1; s0.x = cvtpk(v0[0], v0[1]); s0.y = cvtpk(v0[2], v0[3]); s1.x = cvtpk(v1[0], v1[1]); s1.y = cvtpk(v1[2], v1[3]);
;         *(u32x2*)(orow + 8 * rr) = s0; *(u32x2*)(orow + 32 + 8 * rr) = s1;
;     }
; }
; template <int GRP, bool has_next> __device__ __forceinline__ void att_step(const AttCtx<GRP>& C, AttState<GRP>& S, int s, f32x16& P0, f32x16& P1, f32x16& PN0, f32x16& PN1, u32x4& kreg, u32x4& preg, u32x4& vreg) {
;     ...
;     att_pv<GRP>(S, vf);
;     if (t == 63) {
;         att_finish_head<GRP>(C, S, h);
;         S.o0 = (f32x16){}; S.o1 = (f32x16){}; S.lrun = 0.f; S.mhat = 0.f; S.refnz = 0;
;     }
.Lgqa_nrz1005:
	s_waitcnt lgkmcnt(3)
	v_mfma_f32_32x32x16_bf16 v[16:31], v[232:235], v[216:219], v[16:31]
	ds_read_b128 v[232:235], v146 offset:35904
	s_waitcnt lgkmcnt(3)
	v_mfma_f32_32x32x16_bf16 v[0:15], v[236:239], v[216:219], v[0:15]
	ds_read_b128 v[236:239], v146 offset:40512
	s_waitcnt lgkmcnt(3)
	v_mfma_f32_32x32x16_bf16 v[16:31], v[240:243], v[220:223], v[16:31]
	ds_read_b128 v[240:243], v146 offset:35936
	s_waitcnt lgkmcnt(3)
	v_mfma_f32_32x32x16_bf16 v[0:15], v[244:247], v[220:223], v[0:15]
	ds_read_b128 v[244:247], v146 offset:40544
	s_waitcnt lgkmcnt(3)
	v_mfma_f32_32x32x16_bf16 v[16:31], v[232:235], v[224:227], v[16:31]
	s_waitcnt lgkmcnt(2)
	v_mfma_f32_32x32x16_bf16 v[0:15], v[236:239], v[224:227], v[0:15]
	s_waitcnt lgkmcnt(1)
	v_mfma_f32_32x32x16_bf16 v[16:31], v[240:243], v[228:231], v[16:31]
	s_waitcnt lgkmcnt(0)
	v_mfma_f32_32x32x16_bf16 v[0:15], v[244:247], v[228:231], v[0:15]
	s_cmp_lg_u64 s[86:87], 0
	s_cbranch_scc0 .Lgqa_nofin1006
	s_nop 7
	s_nop 3
	v_mov_b32_e32 v64, v148
	s_nop 1
	v_permlane32_swap_b32_e32 v148, v64
	v_add_f32_e32 v64, v148, v64
	v_div_scale_f32 v65, s[10:11], v64, v64, 1.0
	v_rcp_f32_e32 v66, v65
	s_lshl_b32 s10, s69, 6
	s_ashr_i32 s11, s10, 31
	v_mov_b32_e32 v152, 0
	v_fma_f32 v67, -v65, v66, 1.0
	v_fmac_f32_e32 v66, v67, v66
	v_div_scale_f32 v67, vcc, 1.0, v64, 1.0
	v_mul_f32_e32 v68, v67, v66
	v_fma_f32 v69, -v65, v68, v67
	v_fmac_f32_e32 v68, v69, v66
	v_fma_f32 v65, -v65, v68, v67
	v_div_fmas_f32 v65, v65, v66, v68
	v_div_fixup_f32 v64, v65, v64, 1.0
	v_pk_mul_f32 v[16:17], v[16:17], v[64:65] op_sel_hi:[1,0]
	v_pk_mul_f32 v[18:19], v[18:19], v[64:65] op_sel_hi:[1,0]
	v_pk_mul_f32 v[70:71], v[16:17], v[16:17]
	v_pk_mul_f32 v[68:69], v[18:19], v[18:19]
	v_pk_mul_f32 v[0:1], v[0:1], v[64:65] op_sel_hi:[1,0]
	v_pk_mul_f32 v[2:3], v[2:3], v[64:65] op_sel_hi:[1,0]
	v_pk_mov_b32 v[72:73], v[70:71], v[68:69] op_sel:[1,0]
	v_mov_b32_e32 v71, v69
	v_pk_add_f32 v[68:69], v[72:73], v[70:71]
	v_pk_mul_f32 v[70:71], v[2:3], v[2:3]
	v_pk_mul_f32 v[72:73], v[0:1], v[0:1]
	v_mov_b32_e32 v74, v70
	v_mov_b32_e32 v75, v72
	v_mov_b32_e32 v72, v71
	v_pk_add_f32 v[70:71], v[74:75], v[72:73]
	v_add_f32_e32 v65, v68, v69
	v_add_f32_e32 v65, v71, v65
	v_add_f32_e32 v65, v70, v65
	v_lshl_add_u64 v[66:67], s[10:11], 1, v[142:143]
	v_add_f32_e32 v65, v137, v65
	v_cvt_pk_bf16_f32 v16, v16, v17
	v_cvt_pk_bf16_f32 v17, v18, v19
	v_cvt_pk_bf16_f32 v0, v0, v1
	v_cvt_pk_bf16_f32 v1, v2, v3
	global_store_dwordx2 v[66:67], v[16:17], off offset:1024
	global_store_dwordx2 v[66:67], v[0:1], off offset:1088
	v_pk_mul_f32 v[0:1], v[20:21], v[64:65] op_sel_hi:[1,0]
	v_pk_mul_f32 v[2:3], v[22:23], v[64:65] op_sel_hi:[1,0]
	v_pk_mul_f32 v[4:5], v[4:5], v[64:65] op_sel_hi:[1,0]
	v_pk_mul_f32 v[6:7], v[6:7], v[64:65] op_sel_hi:[1,0]
	v_pk_mul_f32 v[16:17], v[2:3], v[2:3]
	v_pk_mul_f32 v[18:19], v[0:1], v[0:1]
	v_cvt_pk_bf16_f32 v0, v0, v1
	v_cvt_pk_bf16_f32 v1, v2, v3
	v_cvt_pk_bf16_f32 v2, v4, v5
	v_cvt_pk_bf16_f32 v3, v6, v7
	v_pk_mov_b32 v[20:21], v[18:19], v[16:17] op_sel:[1,0]
	v_mov_b32_e32 v19, v17
	global_store_dwordx2 v[66:67], v[0:1], off offset:1040
	global_store_dwordx2 v[66:67], v[2:3], off offset:1104
	v_pk_mul_f32 v[2:3], v[24:25], v[64:65] op_sel_hi:[1,0]
	v_pk_add_f32 v[16:17], v[20:21], v[18:19]
	v_pk_mul_f32 v[18:19], v[6:7], v[6:7]
	v_pk_mul_f32 v[6:7], v[8:9], v[64:65] op_sel_hi:[1,0]
	v_mul_f32_e32 v8, v2, v2
	v_pk_mul_f32 v[0:1], v[26:27], v[64:65] op_sel_hi:[1,0]
	v_pk_fma_f32 v[8:9], v[2:3], v[2:3], v[8:9] op_sel_hi:[1,1,0]
	v_pk_mul_f32 v[20:21], v[4:5], v[4:5]
	v_pk_mul_f32 v[4:5], v[10:11], v[64:65] op_sel_hi:[1,0]
	v_mul_f32_e32 v8, v0, v0
	v_pk_fma_f32 v[10:11], v[0:1], v[0:1], v[8:9] op_sel_hi:[1,1,0]
	v_cvt_pk_bf16_f32 v2, v2, v3
	v_cvt_pk_bf16_f32 v3, v0, v1
	v_cvt_pk_bf16_f32 v0, v6, v7
	v_cvt_pk_bf16_f32 v1, v4, v5
	v_mov_b32_e32 v22, v18
	v_mov_b32_e32 v23, v20
	v_mov_b32_e32 v20, v19
	global_store_dwordx2 v[66:67], v[2:3], off offset:1056
	global_store_dwordx2 v[66:67], v[0:1], off offset:1120
	v_pk_mul_f32 v[0:1], v[28:29], v[64:65] op_sel_hi:[1,0]
	v_pk_add_f32 v[18:19], v[22:23], v[20:21]
	v_pk_mul_f32 v[2:3], v[30:31], v[64:65] op_sel_hi:[1,0]
	v_mov_b32_e32 v21, v6
	v_mov_b32_e32 v6, v1
	v_mul_f32_e32 v8, v2, v2
	v_mul_f32_e32 v10, v3, v3
	v_mov_b32_e32 v20, v0
	v_pk_mul_f32 v[6:7], v[6:7], v[6:7]
	v_pk_add_f32 v[16:17], v[16:17], v[16:17] op_sel:[0,1] op_sel_hi:[1,0]
	v_pk_mul_f32 v[12:13], v[12:13], v[64:65] op_sel_hi:[1,0]
	v_pk_fma_f32 v[6:7], v[20:21], v[20:21], v[6:7]
	v_pk_add_f32 v[8:9], v[8:9], v[10:11]
	v_pk_add_f32 v[16:17], v[18:19], v[16:17] op_sel:[1,0] op_sel_hi:[0,1]
	v_pk_add_f32 v[6:7], v[6:7], v[8:9]
	v_mov_b32_e32 v9, v4
	v_mov_b32_e32 v4, v13
	v_pk_add_f32 v[16:17], v[18:19], v[16:17]
	v_pk_mul_f32 v[14:15], v[14:15], v[64:65] op_sel_hi:[1,0]
	v_mov_b32_e32 v8, v12
	v_pk_mul_f32 v[4:5], v[4:5], v[4:5]
	v_mul_f32_e32 v18, v14, v14
	v_mul_f32_e32 v64, v15, v15
	v_pk_fma_f32 v[4:5], v[8:9], v[8:9], v[4:5]
	v_mov_b32_e32 v19, v16
	v_pk_add_f32 v[4:5], v[4:5], v[6:7]
	v_pk_add_f32 v[6:7], v[18:19], v[64:65]
	v_cvt_pk_bf16_f32 v0, v0, v1
	v_pk_add_f32 v[4:5], v[4:5], v[6:7]
	v_cvt_pk_bf16_f32 v1, v2, v3
	v_cvt_pk_bf16_f32 v2, v12, v13
	v_cvt_pk_bf16_f32 v3, v14, v15
	v_add_f32_e32 v137, v4, v5
	global_store_dwordx2 v[66:67], v[0:1], off offset:1072
	global_store_dwordx2 v[66:67], v[2:3], off offset:1136
	s_mov_b32 s62, 0
	v_mov_b32_e32 v148, 0
	v_mov_b32_e32 v0, 0
	v_mov_b32_e32 v1, v152
	v_mov_b32_e32 v2, v152
	v_mov_b32_e32 v3, v152
	v_mov_b32_e32 v4, v152
	v_mov_b32_e32 v5, v152
	v_mov_b32_e32 v6, v152
	v_mov_b32_e32 v7, v152
	v_mov_b32_e32 v8, v152
	v_mov_b32_e32 v9, v152
	v_mov_b32_e32 v10, v152
	v_mov_b32_e32 v11, v152
	v_mov_b32_e32 v12, v152
	v_mov_b32_e32 v13, v152
	v_mov_b32_e32 v14, v152
	v_mov_b32_e32 v15, v152
	v_mov_b32_e32 v16, 0
	v_mov_b32_e32 v17, v152
	v_mov_b32_e32 v18, v152
	v_mov_b32_e32 v19, v152
	v_mov_b32_e32 v20, v152
	v_mov_b32_e32 v21, v152
	v_mov_b32_e32 v22, v152
	v_mov_b32_e32 v23, v152
	v_mov_b32_e32 v24, v152
	v_mov_b32_e32 v25, v152
	v_mov_b32_e32 v26, v152
	v_mov_b32_e32 v27, v152
	v_mov_b32_e32 v28, v152
	v_mov_b32_e32 v29, v152
	v_mov_b32_e32 v30, v152
	v_mov_b32_e32 v31, v152
; #define LAS __attribute__((address_space(3)))
; __device__ __forceinline__ float xhalf_max(float m) { auto rr = __builtin_amdgcn_permlane32_swap(__float_as_uint(m), __float_as_uint(m), false, false); return fmaxf(__uint_as_float(rr[0]), __uint_as_float(rr[1])); }
; __device__ __forceinline__ float max3f(float a, float b, float c) { float r; asm("v_max3_f32 %0, %1, %2, %3" : "=v"(r) : "v"(a), "v"(b), "v"(c)); return r; }
; __device__ __forceinline__ float max2f(float a, float b) { float r; asm("v_max_f32_e32 %0, %1, %2" : "=v"(r) : "v"(a), "v"(b)); return r; }
; template <int GRP> __device__ __forceinline__ void att_stk(const AttCtx<GRP>& C, int buf, const u32x4& kreg, const u32x4& preg) {
;     *(LAS u32x4*)(C.lds + buf * KBUF + C.kwo) = kreg; if (GRP == 0 && C.tid < 256) *(LAS u32x4*)(C.lds + buf * KBUF + C.pwo) = preg;
; }
; template <int GRP> __device__ __forceinline__ void att_stld(const AttCtx<GRP>& C, int s, u32x4& kreg, u32x4& preg, u32x4& vreg) {
;     constexpr int NSTEP = 256;
;     if (s + 2 < NSTEP) att_stk<GRP>(C, s & 1, kreg, preg);
;     if (s + 1 < NSTEP) att_stv<GRP>(C, (s + 1) & 1, vreg);
;     if (s + 3 < NSTEP) att_ldk<GRP>(C, s + 3, kreg, preg);
;     if (s + 2 < NSTEP) att_ldv<GRP>(C, s + 2, vreg);
; template <int GRP, bool has_next> __device__ __forceinline__ void att_step(const AttCtx<GRP>& C, AttState<GRP>& S, int s, f32x16& P0, f32x16& P1, f32x16& PN0, f32x16& PN1, u32x4& kreg, u32x4& preg, u32x4& vreg) {
;     ...
;     if ((t & 7) == 0) {
;         float ma = max3f(P0[0], P0[1], P0[2]), mb = max3f(P0[3], P0[4], P0[5]), mc = max3f(P1[0], P1[1], P1[2]), md = max3f(P1[3], P1[4], P1[5]);
;         ma = max3f(ma, P0[6], P0[7]); mb = max3f(mb, P0[8], P0[9]); mc = max3f(mc, P1[6], P1[7]); md = max3f(md, P1[8], P1[9]);
;         ma = max3f(ma, P0[10], P0[11]); mb = max3f(mb, P0[12], P0[13]); mc = max3f(mc, P1[10], P1[11]); md = max3f(md, P1[12], P1[13]);
;         ma = max3f(ma, P0[14], P0[15]); mc = max3f(mc, P1[14], P1[15]); ma = max3f(ma, mb, mc); mb = md;
;         const float mx = xhalf_max(max2f(ma, mb));
;         const int up = __any(mx > THR), dn = (t == 0) ? __any(mx < -THR) : 0;
.Lgqa_nofin1006:
	s_add_i32 s88, s61, 4
	s_lshr_b32 s89, s88, 6
	s_add_i32 s89, s89, s60
	s_lshl_b32 s89, s89, 4
	s_and_b32 s89, s89, 0xffffffc0
	s_and_b32 s88, s88, 63
	s_or_b32 s88, s89, s88
	s_lshl_b32 s88, s88, 12
	s_ashr_i32 s89, s88, 31
	s_add_i32 s84, s61, 3
	s_lshr_b32 s85, s84, 6
	s_add_i32 s85, s85, s60
	s_lshl_b32 s85, s85, 4
	s_and_b32 s85, s85, 0xffffffc0
	s_and_b32 s84, s84, 63
	s_or_b32 s84, s85, s84
	s_lshl_b32 s84, s84, 12
	s_ashr_i32 s85, s84, 31
	s_waitcnt vmcnt(1)
	ds_write_b128 v150, v[116:119] offset:13312
	v_lshl_add_u64 v[192:193], s[88:89], 1, v[140:141]
	s_waitcnt vmcnt(0)
	ds_write_b128 v151, v[124:127] offset:26624
	v_lshl_add_u64 v[190:191], s[84:85], 1, v[138:139]
	s_cmpk_gt_u32 s68, 0xfc
	s_cbranch_scc1 .Lgqa_nold1007
	global_load_dwordx4 v[116:119], v[192:193], off
.Lgqa_nold1007:
	global_load_dwordx4 v[120:123], v[190:191], off
	s_add_i32 s10, s61, 2
	s_and_b32 s10, s10, 6
	s_cmp_lg_u32 s10, 0
	s_cbranch_scc1 .Lgqa_nomax1008
	v_max3_f32 v96, v48, v49, v50
	v_max3_f32 v99, v32, v33, v34
	v_max3_f32 v98, v51, v52, v53
	v_max3_f32 v153, v35, v36, v37
	s_add_i32 s10, s61, 2
	s_and_b32 s10, s10, 56
	v_max3_f32 v96, v96, v54, v55
	v_max3_f32 v99, v99, v38, v39
	v_max3_f32 v98, v98, v56, v57
	v_max3_f32 v153, v153, v40, v41
	s_cmp_eq_u32 s10, 0
	v_max3_f32 v96, v96, v58, v59
	v_max3_f32 v99, v99, v42, v43
	v_max3_f32 v98, v98, v60, v61
	v_max3_f32 v153, v153, v44, v45
	s_cselect_b64 s[6:7], -1, 0
	v_max3_f32 v96, v96, v62, v63
	v_max3_f32 v99, v99, v46, v47
	s_cmp_lg_u32 s10, 0
	v_max3_f32 v96, v96, v98, v99
	s_nop 0
	v_max_f32_e32 v96, v96, v153
	s_nop 0
	v_mov_b32_e32 v98, v96
	s_nop 1
	v_permlane32_swap_b32_e32 v96, v98
	v_max_f32_e32 v98, v98, v98
	v_max_f32_e32 v96, v96, v96
	v_max_f32_e32 v96, v96, v98
	v_cmp_lt_f32_e32 vcc, s54, v96
	v_mov_b32_e32 v98, 0
	s_cbranch_scc1 .Lgqa_mx1009
	v_cmp_gt_f32_e64 s[10:11], s55, v96
	s_cmp_lg_u64 s[10:11], 0
	s_cselect_b64 s[10:11], -1, 0
	v_cndmask_b32_e64 v98, 0, 1, s[10:11]

; #define ATT_SUMPACK(j) do { const float e0_ = (j) < 8 ? P0[2 * ((j) & 7)] : P1[2 * ((j) & 7)], e1_ = (j) < 8 ? P0[2 * ((j) & 7) + 1] : P1[2 * ((j) & 7) + 1]; \
;         if ((j) & 1) { rc += e0_; rd += e1_; } else { ra += e0_; rb += e1_; } S.pw[j] = cvtpk(e0_, e1_); } while (0)
; template <int GRP, bool has_next> __device__ __forceinline__ void att_step(const AttCtx<GRP>& C, AttState<GRP>& S, int s, f32x16& P0, f32x16& P1, f32x16& PN0, f32x16& PN1, u32x4& kreg, u32x4& preg, u32x4& vreg) {
;     ...
;     constexpr int NE = NKS - 1;
;     float ra = 0.f, rb = 0.f, rc = 0.f, rd = 0.f;
;     ...
; #pragma unroll
;     for (int c = 1; c < NKS; ++c) {
;         if (has_next) {
;             if (c == NK0) att_kfrag<GRP, NK0, NK1>(C, (s + 1) & 1, kfb);
;             const bf16x8 a0 = c < NK0 ? kfa[2 * c] : kfb[2 * (c - NK0)], a1 = c < NK0 ? kfa[2 * c + 1] : kfb[2 * (c - NK0) + 1];
;             PN0 = __builtin_amdgcn_mfma_f32_32x32x16_bf16(a0, S.qr[c], PN0, 0, 0, 0); PN1 = __builtin_amdgcn_mfma_f32_32x32x16_bf16(a1, S.qr[c], PN1, 0, 0, 0);
;         }
; #pragma unroll
;         for (int j = (c - 1) * 16 / NE; j < c * 16 / NE; ++j) {
;             if (j < 8) { P0[2 * j] = __builtin_amdgcn_exp2f(P0[2 * j]); P0[2 * j + 1] = __builtin_amdgcn_exp2f(P0[2 * j + 1]); }
;             else { P1[2 * (j - 8)] = __builtin_amdgcn_exp2f(P1[2 * (j - 8)]); P1[2 * (j - 8) + 1] = __builtin_amdgcn_exp2f(P1[2 * (j - 8) + 1]); }
;         }
;         if (c > 1) {
; #pragma unroll
;             for (int j = (c - 2) * 16 / NE; j < (c - 1) * 16 / NE; ++j) ATT_SUMPACK(j);
;         }
;         __builtin_amdgcn_sched_barrier(0);
;     }
;     if (has_next && S.refnz && t != 63) { PN0 = __builtin_amdgcn_mfma_f32_32x32x16_bf16(ones, qx, PN0, 0, 0, 0); PN1 = __builtin_amdgcn_mfma_f32_32x32x16_bf16(ones, qx, PN1, 0, 0, 0); }
;     att_vfrag<GRP>(C, s & 1, vf);
; #pragma unroll
;     for (int j = (NE - 1) * 16 / NE; j < 16; ++j) ATT_SUMPACK(j);
; template <int GRP> ...
;     ...
;     for (int s = 0; s < NSTEP - 2; s += 2) { att_step<GRP, true>(C, S, s, pa0, pa1, pb0, pb1, kA, pA, vA); att_step<GRP, true>(C, S, s + 1, pb0, pb1, pa0, pa1, kA, pA, vA); }
;     att_step<GRP, true>(C, S, NSTEP - 2, pa0, pa1, pb0, pb1, kA, pA, vA); att_step<GRP, false>(C, S, NSTEP - 1, pb0, pb1, pa0, pa1, kA, pA, vA);
.Lgqa_nomax1008:
	v_exp_f32_e32 v48, v48
	v_exp_f32_e32 v49, v49
	v_exp_f32_e32 v50, v50
	v_exp_f32_e32 v51, v51
	v_cvt_pk_bf16_f32 v216, v48, v49
	v_exp_f32_e32 v52, v52
	v_exp_f32_e32 v53, v53
	v_cvt_pk_bf16_f32 v217, v50, v51
	v_exp_f32_e32 v54, v54
	v_exp_f32_e32 v55, v55
	v_add_f32_e32 v248, v48, v52
	v_add_f32_e32 v249, v49, v53
	v_cvt_pk_bf16_f32 v218, v52, v53
	v_exp_f32_e32 v56, v56
	v_exp_f32_e32 v57, v57
	v_add_f32_e32 v250, v50, v54
	v_add_f32_e32 v251, v51, v55
	v_cvt_pk_bf16_f32 v219, v54, v55
	v_exp_f32_e32 v58, v58
	v_exp_f32_e32 v59, v59
	v_add_f32_e32 v248, v248, v56
	v_add_f32_e32 v249, v249, v57
	v_cvt_pk_bf16_f32 v220, v56, v57
	v_exp_f32_e32 v60, v60
	v_exp_f32_e32 v61, v61
	v_add_f32_e32 v250, v250, v58
	v_add_f32_e32 v251, v251, v59
	v_cvt_pk_bf16_f32 v221, v58, v59
	v_exp_f32_e32 v62, v62
	v_exp_f32_e32 v63, v63
	v_add_f32_e32 v248, v248, v60
	v_add_f32_e32 v249, v249, v61
	v_cvt_pk_bf16_f32 v222, v60, v61
	v_exp_f32_e32 v32, v32
	v_exp_f32_e32 v33, v33
	v_add_f32_e32 v250, v250, v62
	v_add_f32_e32 v251, v251, v63
	v_cvt_pk_bf16_f32 v223, v62, v63
	v_exp_f32_e32 v34, v34
	v_exp_f32_e32 v35, v35
	v_add_f32_e32 v248, v248, v32
	v_add_f32_e32 v249, v249, v33
	v_cvt_pk_bf16_f32 v224, v32, v33
	v_exp_f32_e32 v36, v36
	v_exp_f32_e32 v37, v37
	v_add_f32_e32 v250, v250, v34
	v_add_f32_e32 v251, v251, v35
	v_cvt_pk_bf16_f32 v225, v34, v35
	v_exp_f32_e32 v38, v38
	v_exp_f32_e32 v39, v39
	v_add_f32_e32 v248, v248, v36
	v_add_f32_e32 v249, v249, v37
	v_cvt_pk_bf16_f32 v226, v36, v37
	v_exp_f32_e32 v40, v40
	v_exp_f32_e32 v41, v41
	v_add_f32_e32 v250, v250, v38
	v_add_f32_e32 v251, v251, v39
	v_cvt_pk_bf16_f32 v227, v38, v39
	v_exp_f32_e32 v42, v42
	v_exp_f32_e32 v43, v43
	v_add_f32_e32 v248, v248, v40
	v_add_f32_e32 v249, v249, v41
	v_cvt_pk_bf16_f32 v228, v40, v41
	v_exp_f32_e32 v44, v44
	v_exp_f32_e32 v45, v45
	v_add_f32_e32 v250, v250, v42
	v_add_f32_e32 v251, v251, v43
	v_cvt_pk_bf16_f32 v229, v42, v43
	v_exp_f32_e32 v46, v46
	v_exp_f32_e32 v47, v47
	v_add_f32_e32 v248, v248, v44
	v_add_f32_e32 v249, v249, v45
	v_cvt_pk_bf16_f32 v230, v44, v45
	v_add_f32_e32 v250, v250, v46
	v_add_f32_e32 v251, v251, v47
	v_cvt_pk_bf16_f32 v231, v46, v47
	v_add_f32_e32 v248, v248, v249
	v_add_f32_e32 v250, v250, v251
	v_add_f32_e32 v248, v248, v250
	v_add_f32_e32 v148, v148, v248
	s_waitcnt lgkmcnt(0)
	s_barrier
	s_cmpk_gt_u32 s61, 0xfb
	s_cbranch_scc1 .Lgqa_L_tail
	s_add_i32 s61, s61, 2
	s_branch .Lgqa_L_loop

; #define ATT_BAR() do { __builtin_amdgcn_sched_barrier(0); asm volatile("s_waitcnt lgkmcnt(0)\n\ts_barrier" ::: "memory"); __builtin_amdgcn_sched_barrier(0); } while (0)
; template <int GRP, bool has_next> __device__ __forceinline__ void att_step(const AttCtx<GRP>& C, AttState<GRP>& S, int s, f32x16& P0, f32x16& P1, f32x16& PN0, f32x16& PN1, u32x4& kreg, u32x4& preg, u32x4& vreg) {
;     ...
;     constexpr int NE = NKS - 1;
;     float ra = 0.f, rb = 0.f, rc = 0.f, rd = 0.f;
;     ...
; #pragma unroll
;     for (int c = 1; c < NKS; ++c) {
;         if (has_next) {
;             if (c == NK0) att_kfrag<GRP, NK0, NK1>(C, (s + 1) & 1, kfb);
;             const bf16x8 a0 = c < NK0 ? kfa[2 * c] : kfb[2 * (c - NK0)], a1 = c < NK0 ? kfa[2 * c + 1] : kfb[2 * (c - NK0) + 1];
;             PN0 = __builtin_amdgcn_mfma_f32_32x32x16_bf16(a0, S.qr[c], PN0, 0, 0, 0); PN1 = __builtin_amdgcn_mfma_f32_32x32x16_bf16(a1, S.qr[c], PN1, 0, 0, 0);
;         }
; #pragma unroll
;         for (int j = (c - 1) * 16 / NE; j < c * 16 / NE; ++j) {
;             if (j < 8) { P0[2 * j] = __builtin_amdgcn_exp2f(P0[2 * j]); P0[2 * j + 1] = __builtin_amdgcn_exp2f(P0[2 * j + 1]); }
;             else { P1[2 * (j - 8)] = __builtin_amdgcn_exp2f(P1[2 * (j - 8)]); P1[2 * (j - 8) + 1] = __builtin_amdgcn_exp2f(P1[2 * (j - 8) + 1]); }
;         }
;         if (c > 1) {
; #pragma unroll
;             for (int j = (c - 2) * 16 / NE; j < (c - 1) * 16 / NE; ++j) ATT_SUMPACK(j);
;         }
;         __builtin_amdgcn_sched_barrier(0);
;     }
;     if (has_next && S.refnz && t != 63) { PN0 = __builtin_amdgcn_mfma_f32_32x32x16_bf16(ones, qx, PN0, 0, 0, 0); PN1 = __builtin_amdgcn_mfma_f32_32x32x16_bf16(ones, qx, PN1, 0, 0, 0); }
;     att_vfrag<GRP>(C, s & 1, vf);
; #pragma unroll
;     for (int j = (NE - 1) * 16 / NE; j < 16; ++j) ATT_SUMPACK(j);
;     ...
;     S.lrun += (ra + rb) + (rc + rd);
;     att_pv<GRP>(S, vf);
;     if (t == 63) {
;         att_finish_head<GRP>(C, S, h);
;         S.o0 = (f32x16){}; S.o1 = (f32x16){}; S.lrun = 0.f; S.mhat = 0.f; S.refnz = 0;
;     }
;     att_stld<GRP>(C, s, kreg, preg, vreg);
;     ATT_BAR();
; template <int GRP> ...
;     ...
;     att_step<GRP, true>(C, S, NSTEP - 2, pa0, pa1, pb0, pb1, kA, pA, vA); att_step<GRP, false>(C, S, NSTEP - 1, pb0, pb1, pa0, pa1, kA, pA, vA);
.Lgqa_nrz1010:
	s_waitcnt lgkmcnt(3)
	v_mfma_f32_32x32x16_bf16 v[16:31], v[232:235], v[216:219], v[16:31]
	ds_read_b128 v[232:235], v146 offset:26688
	s_waitcnt lgkmcnt(3)
	v_mfma_f32_32x32x16_bf16 v[0:15], v[236:239], v[216:219], v[0:15]
	ds_read_b128 v[236:239], v146 offset:31296
	s_waitcnt lgkmcnt(3)
	v_mfma_f32_32x32x16_bf16 v[16:31], v[240:243], v[220:223], v[16:31]
	ds_read_b128 v[240:243], v146 offset:26720
	s_waitcnt lgkmcnt(3)
	v_mfma_f32_32x32x16_bf16 v[0:15], v[244:247], v[220:223], v[0:15]
	ds_read_b128 v[244:247], v146 offset:31328
	s_waitcnt lgkmcnt(3)
	v_mfma_f32_32x32x16_bf16 v[16:31], v[232:235], v[224:227], v[16:31]
	s_waitcnt lgkmcnt(2)
	v_mfma_f32_32x32x16_bf16 v[0:15], v[236:239], v[224:227], v[0:15]
	s_waitcnt lgkmcnt(1)
	v_mfma_f32_32x32x16_bf16 v[16:31], v[240:243], v[228:231], v[16:31]
	s_waitcnt lgkmcnt(0)
	v_mfma_f32_32x32x16_bf16 v[0:15], v[244:247], v[228:231], v[0:15]
	s_waitcnt vmcnt(0)
	ds_write_b128 v147, v[120:123] offset:35840
	v_exp_f32_e32 v80, v80
	v_exp_f32_e32 v81, v81
	v_exp_f32_e32 v82, v82
	v_exp_f32_e32 v83, v83
	v_cvt_pk_bf16_f32 v216, v80, v81
	v_exp_f32_e32 v84, v84
	v_exp_f32_e32 v85, v85
	v_cvt_pk_bf16_f32 v217, v82, v83
	v_exp_f32_e32 v86, v86
	v_exp_f32_e32 v87, v87
	v_add_f32_e32 v248, v80, v84
	v_add_f32_e32 v249, v81, v85
	v_cvt_pk_bf16_f32 v218, v84, v85
	v_exp_f32_e32 v88, v88
	v_exp_f32_e32 v89, v89
	v_add_f32_e32 v250, v82, v86
	v_add_f32_e32 v251, v83, v87
	v_cvt_pk_bf16_f32 v219, v86, v87
	v_exp_f32_e32 v90, v90
	v_exp_f32_e32 v91, v91
	v_add_f32_e32 v248, v248, v88
	v_add_f32_e32 v249, v249, v89
	v_cvt_pk_bf16_f32 v220, v88, v89
	v_exp_f32_e32 v92, v92
	v_exp_f32_e32 v93, v93
	v_add_f32_e32 v250, v250, v90
	v_add_f32_e32 v251, v251, v91
	v_cvt_pk_bf16_f32 v221, v90, v91
	v_exp_f32_e32 v94, v94
	v_exp_f32_e32 v95, v95
	v_add_f32_e32 v248, v248, v92
	v_add_f32_e32 v249, v249, v93
	v_cvt_pk_bf16_f32 v222, v92, v93
	v_exp_f32_e32 v64, v64
	v_exp_f32_e32 v65, v65
	v_add_f32_e32 v250, v250, v94
	v_add_f32_e32 v251, v251, v95
	v_cvt_pk_bf16_f32 v223, v94, v95
	v_exp_f32_e32 v66, v66
	v_exp_f32_e32 v67, v67
	v_add_f32_e32 v248, v248, v64
	v_add_f32_e32 v249, v249, v65
	v_cvt_pk_bf16_f32 v224, v64, v65
	v_exp_f32_e32 v68, v68
	v_exp_f32_e32 v69, v69
	v_add_f32_e32 v250, v250, v66
	v_add_f32_e32 v251, v251, v67
	v_cvt_pk_bf16_f32 v225, v66, v67
	v_exp_f32_e32 v70, v70
	v_exp_f32_e32 v71, v71
	v_add_f32_e32 v248, v248, v68
	v_add_f32_e32 v249, v249, v69
	v_cvt_pk_bf16_f32 v226, v68, v69
	v_exp_f32_e32 v72, v72
	v_exp_f32_e32 v73, v73
	v_add_f32_e32 v250, v250, v70
	v_add_f32_e32 v251, v251, v71
	v_cvt_pk_bf16_f32 v227, v70, v71
	v_exp_f32_e32 v74, v74
	v_exp_f32_e32 v75, v75
	v_add_f32_e32 v248, v248, v72
	v_add_f32_e32 v249, v249, v73
	v_cvt_pk_bf16_f32 v228, v72, v73
	v_exp_f32_e32 v76, v76
	v_exp_f32_e32 v77, v77
	v_add_f32_e32 v250, v250, v74
	v_add_f32_e32 v251, v251, v75
	v_cvt_pk_bf16_f32 v229, v74, v75
	v_exp_f32_e32 v78, v78
	v_exp_f32_e32 v79, v79
	v_add_f32_e32 v248, v248, v76
	v_add_f32_e32 v249, v249, v77
	v_cvt_pk_bf16_f32 v230, v76, v77
	v_add_f32_e32 v250, v250, v78
	v_add_f32_e32 v251, v251, v79
	v_cvt_pk_bf16_f32 v231, v78, v79
	v_add_f32_e32 v248, v248, v249
	v_add_f32_e32 v250, v250, v251
	v_add_f32_e32 v248, v248, v250
	v_add_f32_e32 v148, v148, v248
	s_waitcnt lgkmcnt(0)
	s_barrier
	s_mov_b64 s[86:87], -1
	s_lshr_b32 s10, s61, 6
	s_or_b32 s69, s10, s60
	ds_read_b128 v[232:235], v146 offset:35840
	ds_read_b128 v[236:239], v146 offset:40448
	ds_read_b128 v[240:243], v146 offset:35872
	ds_read_b128 v[244:247], v146 offset:40480
	s_waitcnt lgkmcnt(3)
	v_mfma_f32_32x32x16_bf16 v[16:31], v[232:235], v[216:219], v[16:31]
	ds_read_b128 v[232:235], v146 offset:35904
	s_waitcnt lgkmcnt(3)
	v_mfma_f32_32x32x16_bf16 v[0:15], v[236:239], v[216:219], v[0:15]
	ds_read_b128 v[236:239], v146 offset:40512
	s_waitcnt lgkmcnt(3)
	v_mfma_f32_32x32x16_bf16 v[16:31], v[240:243], v[220:223], v[16:31]
	ds_read_b128 v[240:243], v146 offset:35936
	s_waitcnt lgkmcnt(3)
	v_mfma_f32_32x32x16_bf16 v[0:15], v[244:247], v[220:223], v[0:15]
	ds_read_b128 v[244:247], v146 offset:40544
	s_waitcnt lgkmcnt(3)
	v_mfma_f32_32x32x16_bf16 v[16:31], v[232:235], v[224:227], v[16:31]
	s_waitcnt lgkmcnt(2)
	v_mfma_f32_32x32x16_bf16 v[0:15], v[236:239], v[224:227], v[0:15]
	s_waitcnt lgkmcnt(1)
	v_mfma_f32_32x32x16_bf16 v[16:31], v[240:243], v[228:231], v[16:31]
	s_waitcnt lgkmcnt(0)
	v_mfma_f32_32x32x16_bf16 v[0:15], v[244:247], v[228:231], v[0:15]
	s_cmp_lg_u64 s[86:87], 0
	s_cbranch_scc0 .Lgqa_nofin1011
; __device__ __forceinline__ unsigned cvtpk(float lo, float hi) { f32x2_t v = {lo, hi}; bf16x2_t b = __builtin_convertvector(v, bf16x2_t); return __builtin_bit_cast(unsigned, b); }
; __device__ __forceinline__ float xhalf_sum(float m) { auto rr = __builtin_amdgcn_permlane32_swap(__float_as_uint(m), __float_as_uint(m), false, false); return __uint_as_float(rr[0]) + __uint_as_float(rr[1]); }
; template <int GRP> __device__ __forceinline__ void att_finish_head(const AttCtx<GRP>& C, AttState<GRP>& S, int h) {
;     const float inv = 1.0f / xhalf_sum(S.lrun);
;     bf16_t* orow = C.O + C.qrow * 1024 + GRP * 512 + h * 64 + 4 * C.hi;
; #pragma unroll
;     for (int rr = 0; rr < 4; ++rr) {
;         const f32x4 v0 = (f32x4){S.o0[4 * rr], S.o0[4 * rr + 1], S.o0[4 * rr + 2], S.o0[4 * rr + 3]} * inv, v1 = (f32x4){S.o1[4 * rr], S.o1[4 * rr + 1], S.o1[4 * rr + 2], S.o1[4 * rr + 3]} * inv;
;         S.ssq += (v0[0] * v0[0] + v0[1] * v0[1]) + (v0[2] * v0[2] + v0[3] * v0[3]) + (v1[0] * v1[0] + v1[1] * v1[1]) + (v1[2] * v1[2] + v1[3] * v1[3]);
;         u32x2 s0, s1; s0.x = cvtpk(v0[0], v0[1]); s0.y = cvtpk(v0[2], v0[3]); s1.x = cvtpk(v1[0], v1[1]); s1.y = cvtpk(v1[2], v1[3]);
;         *(u32x2*)(orow + 8 * rr) = s0; *(u32x2*)(orow + 32 + 8 * rr) = s1;
;     }
; }
; template <int GRP, bool has_next> __device__ __forceinline__ void att_step(const AttCtx<GRP>& C, AttState<GRP>& S, int s, f32x16& P0, f32x16& P1, f32x16& PN0, f32x16& PN1, u32x4& kreg, u32x4& preg, u32x4& vreg) {
;     ...
;     if (t == 63) {
;         att_finish_head<GRP>(C, S, h);
;         S.o0 = (f32x16){}; S.o1 = (f32x16){}; S.lrun = 0.f; S.mhat = 0.f; S.refnz = 0;
;     }
	s_nop 7
	s_nop 3
	v_mov_b32_e32 v64, v148
	s_nop 1
	v_permlane32_swap_b32_e32 v148, v64
	v_add_f32_e32 v64, v148, v64
	v_div_scale_f32 v65, s[10:11], v64, v64, 1.0
	v_rcp_f32_e32 v66, v65
	s_lshl_b32 s10, s69, 6
	s_ashr_i32 s11, s10, 31
	v_mov_b32_e32 v152, 0
	v_fma_f32 v67, -v65, v66, 1.0
	v_fmac_f32_e32 v66, v67, v66
	v_div_scale_f32 v67, vcc, 1.0, v64, 1.0
	v_mul_f32_e32 v68, v67, v66
	v_fma_f32 v69, -v65, v68, v67
	v_fmac_f32_e32 v68, v69, v66
	v_fma_f32 v65, -v65, v68, v67
	v_div_fmas_f32 v65, v65, v66, v68
	v_div_fixup_f32 v64, v65, v64, 1.0
	v_pk_mul_f32 v[16:17], v[16:17], v[64:65] op_sel_hi:[1,0]
	v_pk_mul_f32 v[18:19], v[18:19], v[64:65] op_sel_hi:[1,0]
	v_pk_mul_f32 v[70:71], v[16:17], v[16:17]
	v_pk_mul_f32 v[68:69], v[18:19], v[18:19]
	v_pk_mul_f32 v[0:1], v[0:1], v[64:65] op_sel_hi:[1,0]
	v_pk_mul_f32 v[2:3], v[2:3], v[64:65] op_sel_hi:[1,0]
	v_pk_mov_b32 v[72:73], v[70:71], v[68:69] op_sel:[1,0]
	v_mov_b32_e32 v71, v69
	v_pk_add_f32 v[68:69], v[72:73], v[70:71]
	v_pk_mul_f32 v[70:71], v[2:3], v[2:3]
	v_pk_mul_f32 v[72:73], v[0:1], v[0:1]
	v_mov_b32_e32 v74, v70
	v_mov_b32_e32 v75, v72
	v_mov_b32_e32 v72, v71
	v_pk_add_f32 v[70:71], v[74:75], v[72:73]
	v_add_f32_e32 v65, v68, v69
	v_add_f32_e32 v65, v71, v65
	v_add_f32_e32 v65, v70, v65
	v_lshl_add_u64 v[66:67], s[10:11], 1, v[142:143]
	v_add_f32_e32 v65, v137, v65
	v_cvt_pk_bf16_f32 v16, v16, v17
	v_cvt_pk_bf16_f32 v17, v18, v19
	v_cvt_pk_bf16_f32 v0, v0, v1
	v_cvt_pk_bf16_f32 v1, v2, v3
	global_store_dwordx2 v[66:67], v[16:17], off offset:1024
	global_store_dwordx2 v[66:67], v[0:1], off offset:1088
	v_pk_mul_f32 v[0:1], v[20:21], v[64:65] op_sel_hi:[1,0]
	v_pk_mul_f32 v[2:3], v[22:23], v[64:65] op_sel_hi:[1,0]
	v_pk_mul_f32 v[4:5], v[4:5], v[64:65] op_sel_hi:[1,0]
	v_pk_mul_f32 v[6:7], v[6:7], v[64:65] op_sel_hi:[1,0]
	v_pk_mul_f32 v[16:17], v[2:3], v[2:3]
	v_pk_mul_f32 v[18:19], v[0:1], v[0:1]
	v_cvt_pk_bf16_f32 v0, v0, v1
	v_cvt_pk_bf16_f32 v1, v2, v3
	v_cvt_pk_bf16_f32 v2, v4, v5
	v_cvt_pk_bf16_f32 v3, v6, v7
	v_pk_mov_b32 v[20:21], v[18:19], v[16:17] op_sel:[1,0]
	v_mov_b32_e32 v19, v17
	global_store_dwordx2 v[66:67], v[0:1], off offset:1040
	global_store_dwordx2 v[66:67], v[2:3], off offset:1104
	v_pk_mul_f32 v[2:3], v[24:25], v[64:65] op_sel_hi:[1,0]
	v_pk_add_f32 v[16:17], v[20:21], v[18:19]
	v_pk_mul_f32 v[18:19], v[6:7], v[6:7]
	v_pk_mul_f32 v[6:7], v[8:9], v[64:65] op_sel_hi:[1,0]
	v_mul_f32_e32 v8, v2, v2
	v_pk_mul_f32 v[0:1], v[26:27], v[64:65] op_sel_hi:[1,0]
	v_pk_fma_f32 v[8:9], v[2:3], v[2:3], v[8:9] op_sel_hi:[1,1,0]
	v_pk_mul_f32 v[20:21], v[4:5], v[4:5]
	v_pk_mul_f32 v[4:5], v[10:11], v[64:65] op_sel_hi:[1,0]
	v_mul_f32_e32 v8, v0, v0
	v_pk_fma_f32 v[10:11], v[0:1], v[0:1], v[8:9] op_sel_hi:[1,1,0]
	v_cvt_pk_bf16_f32 v2, v2, v3
	v_cvt_pk_bf16_f32 v3, v0, v1
	v_cvt_pk_bf16_f32 v0, v6, v7
	v_cvt_pk_bf16_f32 v1, v4, v5
	v_mov_b32_e32 v22, v18
	v_mov_b32_e32 v23, v20
	v_mov_b32_e32 v20, v19
	global_store_dwordx2 v[66:67], v[2:3], off offset:1056
	global_store_dwordx2 v[66:67], v[0:1], off offset:1120
	v_pk_mul_f32 v[0:1], v[28:29], v[64:65] op_sel_hi:[1,0]
	v_pk_add_f32 v[18:19], v[22:23], v[20:21]
	v_pk_mul_f32 v[2:3], v[30:31], v[64:65] op_sel_hi:[1,0]
	v_mov_b32_e32 v21, v6
	v_mov_b32_e32 v6, v1
	v_mul_f32_e32 v8, v2, v2
	v_mul_f32_e32 v10, v3, v3
	v_mov_b32_e32 v20, v0
	v_pk_mul_f32 v[6:7], v[6:7], v[6:7]
	v_pk_add_f32 v[16:17], v[16:17], v[16:17] op_sel:[0,1] op_sel_hi:[1,0]
	v_pk_mul_f32 v[12:13], v[12:13], v[64:65] op_sel_hi:[1,0]
	v_pk_fma_f32 v[6:7], v[20:21], v[20:21], v[6:7]
	v_pk_add_f32 v[8:9], v[8:9], v[10:11]
	v_pk_add_f32 v[16:17], v[18:19], v[16:17] op_sel:[1,0] op_sel_hi:[0,1]
	v_pk_add_f32 v[6:7], v[6:7], v[8:9]
	v_mov_b32_e32 v9, v4
	v_mov_b32_e32 v4, v13
	v_pk_add_f32 v[16:17], v[18:19], v[16:17]
	v_pk_mul_f32 v[14:15], v[14:15], v[64:65] op_sel_hi:[1,0]
	v_mov_b32_e32 v8, v12
	v_pk_mul_f32 v[4:5], v[4:5], v[4:5]
	v_mul_f32_e32 v18, v14, v14
	v_mul_f32_e32 v64, v15, v15
	v_pk_fma_f32 v[4:5], v[8:9], v[8:9], v[4:5]
	v_mov_b32_e32 v19, v16
	v_pk_add_f32 v[4:5], v[4:5], v[6:7]
	v_pk_add_f32 v[6:7], v[18:19], v[64:65]
	v_cvt_pk_bf16_f32 v0, v0, v1
	v_pk_add_f32 v[4:5], v[4:5], v[6:7]
	v_cvt_pk_bf16_f32 v1, v2, v3
	v_cvt_pk_bf16_f32 v2, v12, v13
	v_cvt_pk_bf16_f32 v3, v14, v15
	v_add_f32_e32 v137, v4, v5
	global_store_dwordx2 v[66:67], v[0:1], off offset:1072
	global_store_dwordx2 v[66:67], v[2:3], off offset:1136
	s_mov_b32 s62, 0
	v_mov_b32_e32 v148, 0
	v_mov_b32_e32 v0, 0
	v_mov_b32_e32 v1, v152
	v_mov_b32_e32 v2, v152
	v_mov_b32_e32 v3, v152
	v_mov_b32_e32 v4, v152
	v_mov_b32_e32 v5, v152
	v_mov_b32_e32 v6, v152
	v_mov_b32_e32 v7, v152
	v_mov_b32_e32 v8, v152
	v_mov_b32_e32 v9, v152
	v_mov_b32_e32 v10, v152
	v_mov_b32_e32 v11, v152
	v_mov_b32_e32 v12, v152
	v_mov_b32_e32 v13, v152
	v_mov_b32_e32 v14, v152
	v_mov_b32_e32 v15, v152
	v_mov_b32_e32 v16, 0
	v_mov_b32_e32 v17, v152
	v_mov_b32_e32 v18, v152
	v_mov_b32_e32 v19, v152
	v_mov_b32_e32 v20, v152
	v_mov_b32_e32 v21, v152
	v_mov_b32_e32 v22, v152
	v_mov_b32_e32 v23, v152
	v_mov_b32_e32 v24, v152
	v_mov_b32_e32 v25, v152
	v_mov_b32_e32 v26, v152
	v_mov_b32_e32 v27, v152
	v_mov_b32_e32 v28, v152
	v_mov_b32_e32 v29, v152
	v_mov_b32_e32 v30, v152
	v_mov_b32_e32 v31, v152
.Lgqa_nofin1011:
	s_waitcnt lgkmcnt(0)
	s_barrier
	v_mov_b32_e32 v0, v137
	s_branch .Lgqa_join

; __device__ __forceinline__ float xhalf_max(float m) { auto rr = __builtin_amdgcn_permlane32_swap(__float_as_uint(m), __float_as_uint(m), false, false); return fmaxf(__uint_as_float(rr[0]), __uint_as_float(rr[1])); }
; __device__ __forceinline__ float max3f(float a, float b, float c) { float r; asm("v_max3_f32 %0, %1, %2, %3" : "=v"(r) : "v"(a), "v"(b), "v"(c)); return r; }
; __device__ __forceinline__ float max2f(float a, float b) { float r; asm("v_max_f32_e32 %0, %1, %2" : "=v"(r) : "v"(a), "v"(b)); return r; }
; template <int GRP> __device__ __forceinline__ void att_stk(const AttCtx<GRP>& C, int buf, const u32x4& kreg, const u32x4& preg) {
;     ...
; }
; template <int GRP> __device__ __forceinline__ void att_stld(const AttCtx<GRP>& C, int s, u32x4& kreg, u32x4& preg, u32x4& vreg) {
;     constexpr int NSTEP = 256;
;     if (s + 2 < NSTEP) att_stk<GRP>(C, s & 1, kreg, preg);
;     if (s + 1 < NSTEP) att_stv<GRP>(C, (s + 1) & 1, vreg);
;     if (s + 3 < NSTEP) att_ldk<GRP>(C, s + 3, kreg, preg);
;     if (s + 2 < NSTEP) att_ldv<GRP>(C, s + 2, vreg);
; template <int GRP, bool has_next> __device__ __forceinline__ void att_step(const AttCtx<GRP>& C, AttState<GRP>& S, int s, f32x16& P0, f32x16& P1, f32x16& PN0, f32x16& PN1, u32x4& kreg, u32x4& preg, u32x4& vreg) {
;     ...
;     if ((t & 7) == 0) {
;         float ma = max3f(P0[0], P0[1], P0[2]), mb = max3f(P0[3], P0[4], P0[5]), mc = max3f(P1[0], P1[1], P1[2]), md = max3f(P1[3], P1[4], P1[5]);
;         ma = max3f(ma, P0[6], P0[7]); mb = max3f(mb, P0[8], P0[9]); mc = max3f(mc, P1[6], P1[7]); md = max3f(md, P1[8], P1[9]);
;         ma = max3f(ma, P0[10], P0[11]); mb = max3f(mb, P0[12], P0[13]); mc = max3f(mc, P1[10], P1[11]); md = max3f(md, P1[12], P1[13]);
;         ma = max3f(ma, P0[14], P0[15]); mc = max3f(mc, P1[14], P1[15]); ma = max3f(ma, mb, mc); mb = md;
;         const float mx = xhalf_max(max2f(ma, mb));
;         const int up = __any(mx > THR), dn = (t == 0) ? __any(mx < -THR) : 0;
.LBB0_808:
	s_add_i32 s88, s61, 3
	s_lshr_b32 s89, s88, 6
	s_add_i32 s89, s89, s60
	s_lshl_b32 s89, s89, 4
	s_and_b32 s89, s89, 0xffffffc0
	s_and_b32 s88, s88, 63
	s_or_b32 s88, s89, s88
	s_lshl_b32 s88, s88, 12
	s_ashr_i32 s89, s88, 31
	s_add_i32 s84, s61, 2
	s_lshr_b32 s85, s84, 6
	s_add_i32 s85, s85, s60
	s_lshl_b32 s85, s85, 4
	s_and_b32 s85, s85, 0xffffffc0
	s_and_b32 s84, s84, 63
	s_or_b32 s84, s85, s84
	s_lshl_b32 s84, s84, 12
	s_ashr_i32 s85, s84, 31
	s_waitcnt vmcnt(1)
	ds_write_b128 v150, v[116:119]
	v_lshl_add_u64 v[192:193], s[88:89], 1, v[140:141]
	s_waitcnt vmcnt(0)
	ds_write_b128 v147, v[120:123] offset:35840
	v_lshl_add_u64 v[190:191], s[84:85], 1, v[138:139]
	global_load_dwordx4 v[116:119], v[192:193], off
	global_load_dwordx4 v[124:127], v[190:191], off
	s_and_b32 s10, s61, 6
	s_cmp_lg_u32 s10, 0
	s_cbranch_scc1 .Lgqa_nomax1012
	v_max3_f32 v96, v48, v49, v50
	v_max3_f32 v99, v32, v33, v34
	v_max3_f32 v98, v51, v52, v53
	v_max3_f32 v153, v35, v36, v37
	s_and_b32 s10, s61, 56
	v_max3_f32 v96, v96, v54, v55
	v_max3_f32 v99, v99, v38, v39
	v_max3_f32 v98, v98, v56, v57
	v_max3_f32 v153, v153, v40, v41
	s_cmp_eq_u32 s10, 0
	v_max3_f32 v96, v96, v58, v59
	v_max3_f32 v99, v99, v42, v43
	v_max3_f32 v98, v98, v60, v61
	v_max3_f32 v153, v153, v44, v45
	s_cselect_b64 s[6:7], -1, 0
	v_max3_f32 v96, v96, v62, v63
	v_max3_f32 v99, v99, v46, v47
	s_cmp_lg_u32 s10, 0
	v_max3_f32 v96, v96, v98, v99
	s_nop 0
	v_max_f32_e32 v96, v96, v153
	s_nop 0
	v_mov_b32_e32 v98, v96
	s_nop 1
	v_permlane32_swap_b32_e32 v96, v98
	v_max_f32_e32 v98, v98, v98
	v_max_f32_e32 v96, v96, v96
	v_max_f32_e32 v96, v96, v98
	v_cmp_lt_f32_e32 vcc, s54, v96
	v_mov_b32_e32 v98, 0
	s_cbranch_scc1 .Lgqa_mx1013
	v_cmp_gt_f32_e64 s[10:11], s55, v96
	s_cmp_lg_u64 s[10:11], 0
	s_cselect_b64 s[10:11], -1, 0
	v_cndmask_b32_e64 v98, 0, 1, s[10:11]

; __device__ __forceinline__ float max2f(float a, float b) { float r; asm("v_max_f32_e32 %0, %1, %2" : "=v"(r) : "v"(a), "v"(b)); return r; }
; template <int GRP, bool has_next> __device__ __forceinline__ void att_step(const AttCtx<GRP>& C, AttState<GRP>& S, int s, f32x16& P0, f32x16& P1, f32x16& PN0, f32x16& PN1, u32x4& kreg, u32x4& preg, u32x4& vreg) {
;     ...
;         att_kfrag<GRP, 0, NK0>(C, (s + 1) & 1, kfa);
;     }
;     if (has_next) { PN0 = __builtin_amdgcn_mfma_f32_32x32x16_bf16(kfa[0], S.qr[0], (f32x16){}, 0, 0, 0); PN1 = __builtin_amdgcn_mfma_f32_32x32x16_bf16(kfa[1], S.qr[0], (f32x16){}, 0, 0, 0); }
;     if ((t & 7) == 0) {
;         float ma = max3f(P0[0], P0[1], P0[2]), mb = max3f(P0[3], P0[4], P0[5]), mc = max3f(P1[0], P1[1], P1[2]), md = max3f(P1[3], P1[4], P1[5]);
;         ma = max3f(ma, P0[6], P0[7]); mb = max3f(mb, P0[8], P0[9]); mc = max3f(mc, P1[6], P1[7]); md = max3f(md, P1[8], P1[9]);
;         ma = max3f(ma, P0[10], P0[11]); mb = max3f(mb, P0[12], P0[13]); mc = max3f(mc, P1[10], P1[11]); md = max3f(md, P1[12], P1[13]);
;         ma = max3f(ma, P0[14], P0[15]); mc = max3f(mc, P1[14], P1[15]); ma = max3f(ma, mb, mc); mb = md;
;         const float mx = xhalf_max(max2f(ma, mb));
;         const int up = __any(mx > THR), dn = (t == 0) ? __any(mx < -THR) : 0;
;         if (up | dn) {
;             const float dl = ceilf((t == 0) ? mx : fmaxf(mx, 0.f));
;             const float f = (t == 0) ? 0.f : __builtin_amdgcn_exp2f(-dl);
;             S.mhat += dl; S.lrun *= f;
; #pragma unroll
;             for (int r = 0; r < 16; ++r) { P0[r] -= dl; P1[r] -= dl; S.o0[r] *= f; S.o1[r] *= f; }
;             S.refnz = __any(S.mhat != 0.f);
;         }
;     }
;     __builtin_amdgcn_sched_barrier(0);
;     const unsigned mbits = (t == 63 || C.hi != 0) ? 0u : (__float_as_uint(-S.mhat) >> 16);
;     const u32x4 qxw = {mbits, 0u, 0u, 0u}; const bf16x8 qx = __builtin_bit_cast(bf16x8, qxw);
;     const bf16x8 ones = {0x3f80, 0x3f80, 0x3f80, 0x3f80, 0x3f80, 0x3f80, 0x3f80, 0x3f80};
;     constexpr int NE = NKS - 1;
;     float ra = 0.f, rb = 0.f, rc = 0.f, rd = 0.f;
;     ...
; #pragma unroll
;     for (int c = 1; c < NKS; ++c) {
;         if (has_next) {
;             if (c == NK0) att_kfrag<GRP, NK0, NK1>(C, (s + 1) & 1, kfb);
;             const bf16x8 a0 = c < NK0 ? kfa[2 * c] : kfb[2 * (c - NK0)], a1 = c < NK0 ? kfa[2 * c + 1] : kfb[2 * (c - NK0) + 1];
.Lgqa_nomax1012:
	v_exp_f32_e32 v48, v48
	v_exp_f32_e32 v49, v49
	v_exp_f32_e32 v50, v50
	v_exp_f32_e32 v51, v51
	v_cvt_pk_bf16_f32 v216, v48, v49
	v_exp_f32_e32 v52, v52
	v_exp_f32_e32 v53, v53
	v_cvt_pk_bf16_f32 v217, v50, v51
	v_exp_f32_e32 v54, v54
	v_exp_f32_e32 v55, v55
	v_add_f32_e32 v248, v48, v52
	v_add_f32_e32 v249, v49, v53
	v_cvt_pk_bf16_f32 v218, v52, v53
	v_exp_f32_e32 v56, v56
	v_exp_f32_e32 v57, v57
	v_add_f32_e32 v250, v50, v54
	v_add_f32_e32 v251, v51, v55
	v_cvt_pk_bf16_f32 v219, v54, v55
	v_exp_f32_e32 v58, v58
	v_exp_f32_e32 v59, v59
	v_add_f32_e32 v248, v248, v56
	v_add_f32_e32 v249, v249, v57
	v_cvt_pk_bf16_f32 v220, v56, v57
	v_exp_f32_e32 v60, v60
	v_exp_f32_e32 v61, v61
	v_add_f32_e32 v250, v250, v58
	v_add_f32_e32 v251, v251, v59
	v_cvt_pk_bf16_f32 v221, v58, v59
	v_exp_f32_e32 v62, v62
	v_exp_f32_e32 v63, v63
	v_add_f32_e32 v248, v248, v60
	v_add_f32_e32 v249, v249, v61
	v_cvt_pk_bf16_f32 v222, v60, v61
	v_exp_f32_e32 v32, v32
	v_exp_f32_e32 v33, v33
	v_add_f32_e32 v250, v250, v62
	v_add_f32_e32 v251, v251, v63
	v_cvt_pk_bf16_f32 v223, v62, v63
	v_exp_f32_e32 v34, v34
	v_exp_f32_e32 v35, v35
	v_add_f32_e32 v248, v248, v32
	v_add_f32_e32 v249, v249, v33
	v_cvt_pk_bf16_f32 v224, v32, v33
	v_exp_f32_e32 v36, v36
	v_exp_f32_e32 v37, v37
	v_add_f32_e32 v250, v250, v34
	v_add_f32_e32 v251, v251, v35
	v_cvt_pk_bf16_f32 v225, v34, v35
	v_exp_f32_e32 v38, v38
	v_exp_f32_e32 v39, v39
	v_add_f32_e32 v248, v248, v36
	v_add_f32_e32 v249, v249, v37
	v_cvt_pk_bf16_f32 v226, v36, v37
	v_exp_f32_e32 v40, v40
	v_exp_f32_e32 v41, v41
	v_add_f32_e32 v250, v250, v38
	v_add_f32_e32 v251, v251, v39
	v_cvt_pk_bf16_f32 v227, v38, v39
	v_exp_f32_e32 v42, v42
	v_exp_f32_e32 v43, v43
	v_add_f32_e32 v248, v248, v40
	v_add_f32_e32 v249, v249, v41
	v_cvt_pk_bf16_f32 v228, v40, v41
	v_exp_f32_e32 v44, v44
	v_exp_f32_e32 v45, v45
	v_add_f32_e32 v250, v250, v42
	v_add_f32_e32 v251, v251, v43
	v_cvt_pk_bf16_f32 v229, v42, v43
	v_exp_f32_e32 v46, v46
	v_exp_f32_e32 v47, v47
	v_add_f32_e32 v248, v248, v44
	v_add_f32_e32 v249, v249, v45
	v_cvt_pk_bf16_f32 v230, v44, v45
	v_add_f32_e32 v250, v250, v46
	v_add_f32_e32 v251, v251, v47
	v_cvt_pk_bf16_f32 v231, v46, v47
	v_add_f32_e32 v248, v248, v249
	v_add_f32_e32 v250, v250, v251
	v_add_f32_e32 v248, v248, v250
	v_add_f32_e32 v148, v148, v248
	ds_read_b128 v[156:159], v149 offset:13312
	ds_read_b128 v[160:163], v149 offset:19968
	ds_read_b128 v[164:167], v149 offset:13344
	ds_read_b128 v[168:171], v149 offset:20000
	ds_read_b128 v[172:175], v149 offset:13376
	ds_read_b128 v[176:179], v149 offset:20032
	s_waitcnt lgkmcnt(5)
	v_mfma_f32_32x32x16_bf16 v[80:95], v[156:159], v[112:115], 0
	ds_read_b128 v[156:159], v149 offset:13408
	s_waitcnt lgkmcnt(5)
	v_mfma_f32_32x32x16_bf16 v[64:79], v[160:163], v[112:115], 0
	ds_read_b128 v[160:163], v149 offset:20064
	s_waitcnt lgkmcnt(5)
	v_mfma_f32_32x32x16_bf16 v[80:95], v[164:167], v[108:111], v[80:95]
	ds_read_b128 v[232:235], v146 offset:26624
	s_waitcnt lgkmcnt(5)
	v_mfma_f32_32x32x16_bf16 v[64:79], v[168:171], v[108:111], v[64:79]
	ds_read_b128 v[236:239], v146 offset:31232
	s_waitcnt lgkmcnt(5)
	v_mfma_f32_32x32x16_bf16 v[80:95], v[172:175], v[104:107], v[80:95]
	ds_read_b128 v[240:243], v146 offset:26656
	s_waitcnt lgkmcnt(5)
	v_mfma_f32_32x32x16_bf16 v[64:79], v[176:179], v[104:107], v[64:79]
	ds_read_b128 v[244:247], v146 offset:31264
	s_waitcnt lgkmcnt(5)
	v_mfma_f32_32x32x16_bf16 v[80:95], v[156:159], v[100:103], v[80:95]
	s_waitcnt lgkmcnt(4)
	v_mfma_f32_32x32x16_bf16 v[64:79], v[160:163], v[100:103], v[64:79]
	s_cmp_eq_u32 s62, 0
	s_cbranch_scc1 .Lgqa_nrz1014
	v_xor_b32_e32 v195, 0x80000000, v152
	s_mov_b32 s18, s16
	s_mov_b32 s19, s16
	s_mov_b32 s17, s16
	v_mov_b64_e32 v[182:183], s[18:19]
	v_mov_b64_e32 v[180:181], s[16:17]
	s_mov_b64 vcc, s[0:1]
	v_cndmask_b32_sdwa v96, v97, v195, vcc dst_sel:DWORD dst_unused:UNUSED_PAD src0_sel:DWORD src1_sel:WORD_1
	v_mov_b32_e32 v98, v97
	v_mov_b32_e32 v99, v97
	s_nop 1
	v_mfma_f32_32x32x16_bf16 v[80:95], v[180:183], v[96:99], v[80:95]
	v_mfma_f32_32x32x16_bf16 v[64:79], v[180:183], v[96:99], v[64:79]
; template <int GRP> __device__ __forceinline__ void att_pv(AttState<GRP>& S, const bf16x8 (&vf)[8]) {
; #pragma unroll
;     for (int ks = 0; ks < 4; ++ks) { const u32x4 w = {S.pw[4 * ks], S.pw[4 * ks + 1], S.pw[4 * ks + 2], S.pw[4 * ks + 3]}; const bf16x8 pb = __builtin_bit_cast(bf16x8, w);
;         S.o0 = __builtin_amdgcn_mfma_f32_32x32x16_bf16(vf[2 * ks], pb, S.o0, 0, 0, 0); S.o1 = __builtin_amdgcn_mfma_f32_32x32x16_bf16(vf[2 * ks + 1], pb, S.o1, 0, 0, 0); }
; }
; template <int GRP, bool has_next> __device__ __forceinline__ void att_step(const AttCtx<GRP>& C, AttState<GRP>& S, int s, f32x16& P0, f32x16& P1, f32x16& PN0, f32x16& PN1, u32x4& kreg, u32x4& preg, u32x4& vreg) {
;     ...
;     if (has_next) {
;         if (t == 63) {
; #pragma unroll
;             for (int ks = 0; ks < NKS; ++ks) S.qr[ks] = *(const bf16x8*)(C.Q + C.qrow * QP + (h + 1) * DK + ks * 16 + C.hi * 8);
;         }
;         att_kfrag<GRP, 0, NK0>(C, (s + 1) & 1, kfa);
;     }
;     if (has_next) { PN0 = __builtin_amdgcn_mfma_f32_32x32x16_bf16(kfa[0], S.qr[0], (f32x16){}, 0, 0, 0); PN1 = __builtin_amdgcn_mfma_f32_32x32x16_bf16(kfa[1], S.qr[0], (f32x16){}, 0, 0, 0); }
;     if ((t & 7) == 0) {
;         float ma = max3f(P0[0], P0[1], P0[2]), mb = max3f(P0[3], P0[4], P0[5]), mc = max3f(P1[0], P1[1], P1[2]), md = max3f(P1[3], P1[4], P1[5]);
;         ma = max3f(ma, P0[6], P0[7]); mb = max3f(mb, P0[8], P0[9]); mc = max3f(mc, P1[6], P1[7]); md = max3f(md, P1[8], P1[9]);
;         ma = max3f(ma, P0[10], P0[11]); mb = max3f(mb, P0[12], P0[13]); mc = max3f(mc, P1[10], P1[11]); md = max3f(md, P1[12], P1[13]);
;         ma = max3f(ma, P0[14], P0[15]); mc = max3f(mc, P1[14], P1[15]); ma = max3f(ma, mb, mc); mb = md;
;         const float mx = xhalf_max(max2f(ma, mb));
;         const int up = __any(mx > THR), dn = (t == 0) ? __any(mx < -THR) : 0;
;         if (up | dn) {
;             const float dl = ceilf((t == 0) ? mx : fmaxf(mx, 0.f));
;             const float f = (t == 0) ? 0.f : __builtin_amdgcn_exp2f(-dl);
;             S.mhat += dl; S.lrun *= f;
; #pragma unroll
;             for (int r = 0; r < 16; ++r) { P0[r] -= dl; P1[r] -= dl; S.o0[r] *= f; S.o1[r] *= f; }
;             S.refnz = __any(S.mhat != 0.f);
;         }
;     }
;     __builtin_amdgcn_sched_barrier(0);
;     const unsigned mbits = (t == 63 || C.hi != 0) ? 0u : (__float_as_uint(-S.mhat) >> 16);
.Lgqa_nrz1014:
	s_waitcnt lgkmcnt(3)
	v_mfma_f32_32x32x16_bf16 v[16:31], v[232:235], v[216:219], v[16:31]
	ds_read_b128 v[232:235], v146 offset:26688
	s_waitcnt lgkmcnt(3)
	v_mfma_f32_32x32x16_bf16 v[0:15], v[236:239], v[216:219], v[0:15]
	ds_read_b128 v[236:239], v146 offset:31296
	s_waitcnt lgkmcnt(3)
	v_mfma_f32_32x32x16_bf16 v[16:31], v[240:243], v[220:223], v[16:31]
	ds_read_b128 v[240:243], v146 offset:26720
	s_waitcnt lgkmcnt(3)
	v_mfma_f32_32x32x16_bf16 v[0:15], v[244:247], v[220:223], v[0:15]
	ds_read_b128 v[244:247], v146 offset:31328
	s_waitcnt lgkmcnt(3)
	v_mfma_f32_32x32x16_bf16 v[16:31], v[232:235], v[224:227], v[16:31]
	s_waitcnt lgkmcnt(2)
	v_mfma_f32_32x32x16_bf16 v[0:15], v[236:239], v[224:227], v[0:15]
	s_waitcnt lgkmcnt(1)
	v_mfma_f32_32x32x16_bf16 v[16:31], v[240:243], v[228:231], v[16:31]
	s_waitcnt lgkmcnt(0)
	v_mfma_f32_32x32x16_bf16 v[0:15], v[244:247], v[228:231], v[0:15]
	s_waitcnt lgkmcnt(0)
	s_barrier
	s_add_i32 s68, s61, 1
	s_lshr_b32 s10, s61, 6
	s_or_b32 s69, s10, s60
	s_and_b32 s10, s68, 63
	s_cmp_eq_u32 s10, 63
	s_cselect_b64 s[86:87], -1, 0
	s_add_i32 s88, s61, 4
	s_lshr_b32 s89, s88, 6
	s_add_i32 s89, s89, s60
	s_lshl_b32 s89, s89, 4
	s_and_b32 s89, s89, 0xffffffc0
	s_and_b32 s88, s88, 63
	s_or_b32 s88, s89, s88
	s_lshl_b32 s88, s88, 12
	s_ashr_i32 s89, s88, 31
	s_add_i32 s84, s61, 3
	s_lshr_b32 s85, s84, 6
	s_add_i32 s85, s85, s60
	s_lshl_b32 s85, s85, 4
	s_and_b32 s85, s85, 0xffffffc0
	s_and_b32 s84, s84, 63
	s_or_b32 s84, s85, s84
	s_lshl_b32 s84, s84, 12
	s_ashr_i32 s85, s84, 31
	s_waitcnt vmcnt(1)
	ds_write_b128 v150, v[116:119] offset:13312
	v_lshl_add_u64 v[192:193], s[88:89], 1, v[140:141]
	s_waitcnt vmcnt(0)
	ds_write_b128 v151, v[124:127] offset:26624
	v_lshl_add_u64 v[190:191], s[84:85], 1, v[138:139]
	s_cmpk_gt_u32 s68, 0xfc
	s_cbranch_scc1 .Lgqa_nold1015
	global_load_dwordx4 v[116:119], v[192:193], off
.Lgqa_nold1015:
	global_load_dwordx4 v[120:123], v[190:191], off
	v_exp_f32_e32 v80, v80
	v_exp_f32_e32 v81, v81
	v_exp_f32_e32 v82, v82
	v_exp_f32_e32 v83, v83
	v_cvt_pk_bf16_f32 v216, v80, v81
	v_exp_f32_e32 v84, v84
	v_exp_f32_e32 v85, v85
	v_cvt_pk_bf16_f32 v217, v82, v83
	v_exp_f32_e32 v86, v86
	v_exp_f32_e32 v87, v87
	v_add_f32_e32 v248, v80, v84
	v_add_f32_e32 v249, v81, v85
	v_cvt_pk_bf16_f32 v218, v84, v85
	v_exp_f32_e32 v88, v88
	v_exp_f32_e32 v89, v89
	v_add_f32_e32 v250, v82, v86
	v_add_f32_e32 v251, v83, v87
	v_cvt_pk_bf16_f32 v219, v86, v87
	v_exp_f32_e32 v90, v90
	v_exp_f32_e32 v91, v91
	v_add_f32_e32 v248, v248, v88
	v_add_f32_e32 v249, v249, v89
	v_cvt_pk_bf16_f32 v220, v88, v89
	v_exp_f32_e32 v92, v92
	v_exp_f32_e32 v93, v93
	v_add_f32_e32 v250, v250, v90
	v_add_f32_e32 v251, v251, v91
	v_cvt_pk_bf16_f32 v221, v90, v91
	v_exp_f32_e32 v94, v94
	v_exp_f32_e32 v95, v95
	v_add_f32_e32 v248, v248, v92
	v_add_f32_e32 v249, v249, v93
	v_cvt_pk_bf16_f32 v222, v92, v93
	v_exp_f32_e32 v64, v64
	v_exp_f32_e32 v65, v65
	v_add_f32_e32 v250, v250, v94
	v_add_f32_e32 v251, v251, v95
	v_cvt_pk_bf16_f32 v223, v94, v95
	v_exp_f32_e32 v66, v66
	v_exp_f32_e32 v67, v67
	v_add_f32_e32 v248, v248, v64
	v_add_f32_e32 v249, v249, v65
	v_cvt_pk_bf16_f32 v224, v64, v65
	v_exp_f32_e32 v68, v68
	v_exp_f32_e32 v69, v69
	v_add_f32_e32 v250, v250, v66
	v_add_f32_e32 v251, v251, v67
	v_cvt_pk_bf16_f32 v225, v66, v67
	v_exp_f32_e32 v70, v70
	v_exp_f32_e32 v71, v71
	v_add_f32_e32 v248, v248, v68
	v_add_f32_e32 v249, v249, v69
	v_cvt_pk_bf16_f32 v226, v68, v69
	v_exp_f32_e32 v72, v72
	v_exp_f32_e32 v73, v73
	v_add_f32_e32 v250, v250, v70
	v_add_f32_e32 v251, v251, v71
	v_cvt_pk_bf16_f32 v227, v70, v71
	v_exp_f32_e32 v74, v74
	v_exp_f32_e32 v75, v75
	v_add_f32_e32 v248, v248, v72
	v_add_f32_e32 v249, v249, v73
	v_cvt_pk_bf16_f32 v228, v72, v73
	v_exp_f32_e32 v76, v76
	v_exp_f32_e32 v77, v77
	v_add_f32_e32 v250, v250, v74
	v_add_f32_e32 v251, v251, v75
	v_cvt_pk_bf16_f32 v229, v74, v75
	v_exp_f32_e32 v78, v78
	v_exp_f32_e32 v79, v79
	v_add_f32_e32 v248, v248, v76
	v_add_f32_e32 v249, v249, v77
	v_cvt_pk_bf16_f32 v230, v76, v77
	v_add_f32_e32 v250, v250, v78
	v_add_f32_e32 v251, v251, v79
	v_cvt_pk_bf16_f32 v231, v78, v79
	v_add_f32_e32 v248, v248, v249
	v_add_f32_e32 v250, v250, v251
	v_add_f32_e32 v248, v248, v250
	v_add_f32_e32 v148, v148, v248
	s_cmp_lg_u64 s[86:87], 0
	s_cbranch_scc0 .Lgqa_noq1016
	s_lshl_b32 s88, s69, 6
	s_ashr_i32 s89, s88, 31
	v_lshl_add_u64 v[192:193], s[88:89], 1, v[144:145]
	global_load_dwordx4 v[112:115], v[192:193], off offset:128
	global_load_dwordx4 v[108:111], v[192:193], off offset:160
	global_load_dwordx4 v[104:107], v[192:193], off offset:192
	global_load_dwordx4 v[100:103], v[192:193], off offset:224
	s_waitcnt vmcnt(0)

; #define ATT_BAR() do { __builtin_amdgcn_sched_barrier(0); asm volatile("s_waitcnt lgkmcnt(0)\n\ts_barrier" ::: "memory"); __builtin_amdgcn_sched_barrier(0); } while (0)
; template <int GRP, bool has_next> __device__ __forceinline__ void att_step(const AttCtx<GRP>& C, AttState<GRP>& S, int s, f32x16& P0, f32x16& P1, f32x16& PN0, f32x16& PN1, u32x4& kreg, u32x4& preg, u32x4& vreg) {
;     ...
;     ATT_BAR();
; }
; template <int GRP> ...
;     ...
;     for (int s = 0; s < NSTEP - 2; s += 2) { att_step<GRP, true>(C, S, s, pa0, pa1, pb0, pb1, kA, pA, vA); att_step<GRP, true>(C, S, s + 1, pb0, pb1, pa0, pa1, kA, pA, vA); }
.Lgqa_nofin1018:
	s_waitcnt lgkmcnt(0)
	s_barrier
	s_cmpk_gt_u32 s61, 0xfb
	s_cbranch_scc1 .LBB0_825
	s_add_i32 s61, s61, 2
	s_branch .LBB0_808

; __device__ __forceinline__ float xhalf_sum(float m) { auto rr = __builtin_amdgcn_permlane32_swap(__float_as_uint(m), __float_as_uint(m), false, false); return __uint_as_float(rr[0]) + __uint_as_float(rr[1]); }
; template <int GRP> ...
;     ...
;     __builtin_amdgcn_s_setprio(0);
;     const float ssq = xhalf_sum(S.ssq);
;     if (hi == 0) RS[C.qrow * 4 + GRP * 2 + hh] = ssq;
.Lgqa_join:
	s_setprio 0
	v_mov_b32_e32 v1, v0
	s_nop 1
	v_permlane32_swap_b32_e32 v0, v1
	s_and_saveexec_b64 s[6:7], s[0:1]
	s_cbranch_execz .LBB0_764
	v_add_f32_e32 v2, v0, v1
	v_lshl_add_u64 v[0:1], v[132:133], 4, s[46:47]
	s_ashr_i32 s67, s66, 31
	v_lshl_add_u64 v[0:1], s[66:67], 2, v[0:1]
	global_store_dword v[0:1], v2, off offset:8
	s_branch .LBB0_764
